# write-through (sc1) stores also for phase-0 bf16 x, mix outputs and attention outputs
# baseline (speedup 1.0000x reference)
; __device__ __forceinline__ unsigned cvt_pk(float lo, float hi) { unsigned r; asm volatile("v_cvt_pk_bf16_f32 %0, %1, %2" : "=v"(r) : "v"(lo), "v"(hi)); return r; }
; __device__ void phase_prep(const Params& p, unsigned char* smem) {
;     ...
;     for (size_t i = (size_t)blockIdx.x * 512 + tid; i < n8; i += (size_t)gridDim.x * 512) {
;         const float* src = i < half8 ? p.xp + i * 8 : p.xs + (i - half8) * 8;
;         const f32x4 a = __builtin_nontemporal_load((const f32x4*)src), b = __builtin_nontemporal_load((const f32x4*)(src + 4));
;         u32x4 w; w.x = cvt_pk(a[0], a[1]); w.y = cvt_pk(a[2], a[3]); w.z = cvt_pk(b[0], b[1]); w.w = cvt_pk(b[2], b[3]);
;         *(u32x4*)(XB + i * 8) = w;
;     }
.LBB0_20:
	v_lshl_add_u64 v[8:9], s[36:37], 0, v[6:7]
	v_lshl_add_u64 v[10:11], s[12:13], 0, v[6:7]
	v_cmp_gt_u64_e32 vcc, s[18:19], v[2:3]
	v_lshl_add_u64 v[2:3], v[2:3], 0, s[8:9]
	v_lshl_add_u64 v[6:7], v[6:7], 0, s[14:15]
	v_cndmask_b32_e32 v13, v11, v9, vcc
	v_cndmask_b32_e32 v12, v10, v8, vcc
	global_load_dwordx4 v[8:11], v[12:13], off nt
	s_nop 0
	global_load_dwordx4 v[12:15], v[12:13], off offset:16 nt
	v_cmp_lt_u64_e32 vcc, s[20:21], v[2:3]
	s_or_b64 s[16:17], vcc, s[16:17]
	s_waitcnt vmcnt(1)
	v_cvt_pk_bf16_f32 v8, v8, v9
	v_cvt_pk_bf16_f32 v9, v10, v11
	s_waitcnt vmcnt(0)
	v_cvt_pk_bf16_f32 v10, v12, v13
	v_cvt_pk_bf16_f32 v11, v14, v15
	global_store_dwordx4 v[4:5], v[8:11], off sc1
	v_lshl_add_u64 v[4:5], v[4:5], 0, s[10:11]
	s_andn2_b64 exec, exec, s[16:17]
	s_cbranch_execnz .LBB0_20

; template <int NB> __device__ __forceinline__ void mm16(f32x4 (&acc)[NB], const unsigned char* Xs, const bf16x8 (&yf)[4], int lane) {
;     const int i = lane & 15, kq = lane >> 4;
; #pragma unroll
;     for (int ks = 0; ks < 4; ++ks)
; #pragma unroll
;         for (int nb = 0; nb < NB; ++nb) {
;             const bf16x8 x = *(const bf16x8*)(Xs + swz(nb * 16 + i, ks * 4 + kq));
;             acc[nb] = __builtin_amdgcn_mfma_f32_16x16x32_bf16(x, yf[ks], acc[nb], 0, 0, 0);
;             if ((nb & 3) == 3) __builtin_amdgcn_sched_barrier(0);
;         }
; }
; __device__ void phase_mix(const Params& p, unsigned char* smem) {
;     ...
;             bf16x8 af[4]; ldfrag(af, As, wid, lane);
;             f32x4 acc[8];
; #pragma unroll
;             for (int nb = 0; nb < 8; ++nb) acc[nb] = (f32x4){0.f, 0.f, 0.f, 0.f};
;             mm16<8>(acc, Bs, af, lane);
.LBB0_144:
	s_or_b64 exec, exec, s[22:23]
	v_add_u32_e32 v206, v82, v104
	ds_read_b128 v[20:23], v206 offset:32768
	ds_read_b128 v[24:27], v206 offset:36864
	ds_read_b128 v[28:31], v178
	ds_read_b128 v[32:35], v179
	ds_read_b128 v[36:39], v206 offset:40960
	ds_read_b128 v[182:185], v206 offset:45056
	ds_read_b128 v[186:189], v180
	ds_read_b128 v[190:193], v181
	s_waitcnt lgkmcnt(5)
	v_mfma_f32_16x16x32_bf16 v[20:23], v[20:23], v[28:31], 0
	v_mfma_f32_16x16x32_bf16 v[24:27], v[24:27], v[28:31], 0
	s_waitcnt lgkmcnt(3)
	v_mfma_f32_16x16x32_bf16 v[36:39], v[36:39], v[28:31], 0
	s_waitcnt lgkmcnt(2)
	v_mfma_f32_16x16x32_bf16 v[182:185], v[182:185], v[28:31], 0
	ds_read_b128 v[194:197], v206 offset:49152
	ds_read_b128 v[198:201], v206 offset:53248
	ds_read_b128 v[202:205], v206 offset:57344
	ds_read_b128 v[206:209], v206 offset:61440
	s_waitcnt lgkmcnt(3)
	v_mfma_f32_16x16x32_bf16 v[194:197], v[194:197], v[28:31], 0
	s_waitcnt lgkmcnt(2)
	v_mfma_f32_16x16x32_bf16 v[198:201], v[198:201], v[28:31], 0
	s_waitcnt lgkmcnt(1)
	v_mfma_f32_16x16x32_bf16 v[202:205], v[202:205], v[28:31], 0
	s_waitcnt lgkmcnt(0)
	v_mfma_f32_16x16x32_bf16 v[28:31], v[206:209], v[28:31], 0
	v_add_u32_e32 v214, v82, v77
	ds_read_b128 v[206:209], v214 offset:32768
	ds_read_b128 v[210:213], v214 offset:36864
	s_waitcnt lgkmcnt(1)
	v_mfma_f32_16x16x32_bf16 v[20:23], v[206:209], v[32:35], v[20:23]
	ds_read_b128 v[206:209], v214 offset:40960
	s_waitcnt lgkmcnt(1)
	v_mfma_f32_16x16x32_bf16 v[24:27], v[210:213], v[32:35], v[24:27]
	ds_read_b128 v[210:213], v214 offset:45056
	s_waitcnt lgkmcnt(1)
	v_mfma_f32_16x16x32_bf16 v[36:39], v[206:209], v[32:35], v[36:39]
	s_waitcnt lgkmcnt(0)
	v_mfma_f32_16x16x32_bf16 v[182:185], v[210:213], v[32:35], v[182:185]
	ds_read_b128 v[206:209], v214 offset:49152
	ds_read_b128 v[210:213], v214 offset:53248
	s_waitcnt lgkmcnt(1)
	v_mfma_f32_16x16x32_bf16 v[194:197], v[206:209], v[32:35], v[194:197]
	ds_read_b128 v[206:209], v214 offset:57344
	s_waitcnt lgkmcnt(1)
	v_mfma_f32_16x16x32_bf16 v[198:201], v[210:213], v[32:35], v[198:201]
	ds_read_b128 v[210:213], v214 offset:61440
	s_waitcnt lgkmcnt(1)
	v_mfma_f32_16x16x32_bf16 v[202:205], v[206:209], v[32:35], v[202:205]
	s_waitcnt lgkmcnt(0)
	v_mfma_f32_16x16x32_bf16 v[28:31], v[210:213], v[32:35], v[28:31]
	v_add_u32_e32 v210, v82, v78
	ds_read_b128 v[32:35], v210 offset:32768
	ds_read_b128 v[206:209], v210 offset:36864
	s_waitcnt lgkmcnt(1)
	v_mfma_f32_16x16x32_bf16 v[20:23], v[32:35], v[186:189], v[20:23]
	ds_read_b128 v[32:35], v210 offset:40960
	s_waitcnt lgkmcnt(1)
	v_mfma_f32_16x16x32_bf16 v[24:27], v[206:209], v[186:189], v[24:27]
	ds_read_b128 v[206:209], v210 offset:45056
	s_waitcnt lgkmcnt(1)
	v_mfma_f32_16x16x32_bf16 v[32:35], v[32:35], v[186:189], v[36:39]
	s_waitcnt lgkmcnt(0)
	v_mfma_f32_16x16x32_bf16 v[36:39], v[206:209], v[186:189], v[182:185]
	s_nop 2
	ds_read_b128 v[182:185], v210 offset:49152
	ds_read_b128 v[206:209], v210 offset:53248
	s_waitcnt lgkmcnt(1)
	v_mfma_f32_16x16x32_bf16 v[182:185], v[182:185], v[186:189], v[194:197]
	s_nop 2
	ds_read_b128 v[194:197], v210 offset:57344
	s_waitcnt lgkmcnt(1)
	v_mfma_f32_16x16x32_bf16 v[198:201], v[206:209], v[186:189], v[198:201]
	ds_read_b128 v[206:209], v210 offset:61440
	s_waitcnt lgkmcnt(1)
	v_mfma_f32_16x16x32_bf16 v[194:197], v[194:197], v[186:189], v[202:205]
	s_waitcnt lgkmcnt(0)
	v_mfma_f32_16x16x32_bf16 v[186:189], v[206:209], v[186:189], v[28:31]
	v_add_u32_e32 v214, v82, v79
	s_nop 1
	ds_read_b128 v[28:31], v214 offset:32768
	ds_read_b128 v[202:205], v214 offset:36864
	s_waitcnt lgkmcnt(1)
	v_mfma_f32_16x16x32_bf16 v[206:209], v[28:31], v[190:193], v[20:23]
	s_nop 2
	ds_read_b128 v[20:23], v214 offset:40960
	s_waitcnt lgkmcnt(1)
	v_mfma_f32_16x16x32_bf16 v[202:205], v[202:205], v[190:193], v[24:27]
	s_nop 2
	ds_read_b128 v[24:27], v214 offset:45056
	s_waitcnt lgkmcnt(1)
	v_mfma_f32_16x16x32_bf16 v[210:213], v[20:23], v[190:193], v[32:35]
	s_waitcnt lgkmcnt(0)
	v_mfma_f32_16x16x32_bf16 v[36:39], v[24:27], v[190:193], v[36:39]
	ds_read_b128 v[20:23], v214 offset:49152
	ds_read_b128 v[24:27], v214 offset:53248
	s_waitcnt lgkmcnt(1)
	v_mfma_f32_16x16x32_bf16 v[32:35], v[20:23], v[190:193], v[182:185]
	ds_read_b128 v[20:23], v214 offset:57344
	s_nop 1
	ds_read_b128 v[182:185], v214 offset:61440
	s_waitcnt lgkmcnt(2)
	v_mfma_f32_16x16x32_bf16 v[28:31], v[24:27], v[190:193], v[198:201]
	s_waitcnt lgkmcnt(1)
	v_mfma_f32_16x16x32_bf16 v[24:27], v[20:23], v[190:193], v[194:197]
	s_waitcnt lgkmcnt(0)
; __device__ __forceinline__ unsigned cvt_pk(float lo, float hi) { unsigned r; asm volatile("v_cvt_pk_bf16_f32 %0, %1, %2" : "=v"(r) : "v"(lo), "v"(hi)); return r; }
; __device__ __forceinline__ float bflo(unsigned w) { return __uint_as_float(w << 16); }
; __device__ __forceinline__ float bfhi(unsigned w) { return __uint_as_float(w & 0xffff0000u); }
; __device__ __forceinline__ float silu(float x) { return x * sigm(x); }
; __device__ void phase_mix(const Params& p, unsigned char* smem) {
;     ...
; #pragma unroll
;             for (int nb = 0; nb < 8; ++nb) { const int d = nb * 16 + kq * 4;
;                 const u32x2 za = zreg[nb]; const f32x4 ps = *(const f32x4*)(p.pool_scale + g * 128 + d);
;                 u32x2 o; o.x = cvt_pk(acc[nb][0] * ps[0] * silu(bflo(za.x)), acc[nb][1] * ps[1] * silu(bfhi(za.x)));
;                 o.y = cvt_pk(acc[nb][2] * ps[2] * silu(bflo(za.y)), acc[nb][3] * ps[3] * silu(bfhi(za.y)));
;                 *(u32x2*)(CAT0 + r * 1024 + g * 128 + d) = o; }
	v_mfma_f32_16x16x32_bf16 v[20:23], v[182:185], v[190:193], v[186:189]
	v_mov_b64_e32 v[182:183], v[216:217]
	v_mov_b64_e32 v[184:185], v[218:219]
	s_nop 0
	v_lshlrev_b32_e32 v186, 16, v66
	v_lshlrev_b32_e32 v190, 16, v67
	v_mul_f32_e32 v187, 0xbfb8aa3b, v186
	v_mul_f32_e32 v188, 0xbfb8aa3b, v190
	v_exp_f32_e32 v187, v187
	v_exp_f32_e32 v188, v188
	v_mov_b32_e32 v189, v206
	v_mov_b32_e32 v193, v208
	v_add_f32_e32 v187, 1.0, v187
	v_add_f32_e32 v191, 1.0, v188
	v_rcp_f32_e32 v188, v187
	v_rcp_f32_e32 v192, v191
	v_lshlrev_b64 v[68:69], 11, v[68:69]
	v_lshl_add_u64 v[68:69], v[50:51], 0, v[68:69]
	s_and_b64 vcc, exec, s[20:21]
	s_mov_b32 s34, s0
	v_mov_b32_e32 v187, v182
	v_and_b32_e32 v182, 0xffff0000, v66
	v_mov_b32_e32 v191, v184
	v_and_b32_e32 v184, 0xffff0000, v67
	v_mul_f32_e32 v66, 0xbfb8aa3b, v182
	v_mul_f32_e32 v67, 0xbfb8aa3b, v184
	v_exp_f32_e32 v194, v66
	v_exp_f32_e32 v195, v67
	v_pk_mul_f32 v[66:67], v[188:189], v[186:187]
	v_pk_mul_f32 v[186:187], v[192:193], v[190:191]
	v_add_f32_e32 v188, 1.0, v194
	v_add_f32_e32 v189, 1.0, v195
	v_rcp_f32_e32 v206, v188
	v_rcp_f32_e32 v208, v189
	v_mul_f32_e32 v188, v66, v67
	v_mul_f32_e32 v186, v186, v187
	v_pk_mul_f32 v[66:67], v[206:207], v[182:183]
	v_pk_mul_f32 v[182:183], v[208:209], v[184:185]
	v_mul_f32_e32 v66, v66, v67
	v_mul_f32_e32 v67, v182, v183
	v_cvt_pk_bf16_f32 v66, v188, v66
	v_cvt_pk_bf16_f32 v67, v186, v67
	global_store_dwordx2 v[68:69], v[66:67], off sc1
	v_mov_b64_e32 v[182:183], v[220:221]
	v_mov_b64_e32 v[184:185], v[222:223]
	v_lshlrev_b32_e32 v66, 16, v64
	v_lshlrev_b32_e32 v186, 16, v65
	v_mul_f32_e32 v67, 0xbfb8aa3b, v66
	v_mul_f32_e32 v187, 0xbfb8aa3b, v186
	v_exp_f32_e32 v67, v67
	v_exp_f32_e32 v187, v187
	v_mov_b32_e32 v189, v202
	v_mov_b32_e32 v191, v204
	v_add_f32_e32 v67, 1.0, v67
	v_add_f32_e32 v187, 1.0, v187
	v_rcp_f32_e32 v188, v67
	v_rcp_f32_e32 v190, v187
	v_mov_b32_e32 v67, v182
	v_and_b32_e32 v182, 0xffff0000, v64
	v_mov_b32_e32 v187, v184
	v_and_b32_e32 v184, 0xffff0000, v65
	v_mul_f32_e32 v64, 0xbfb8aa3b, v182
	v_mul_f32_e32 v65, 0xbfb8aa3b, v184
	v_exp_f32_e32 v192, v64
	v_exp_f32_e32 v193, v65
	v_pk_mul_f32 v[64:65], v[188:189], v[66:67]
	v_pk_mul_f32 v[66:67], v[190:191], v[186:187]
	v_add_f32_e32 v186, 1.0, v192
	v_add_f32_e32 v187, 1.0, v193
	v_rcp_f32_e32 v202, v186
	v_rcp_f32_e32 v204, v187
	v_mul_f32_e32 v186, v64, v65
	v_mul_f32_e32 v187, v66, v67
	v_pk_mul_f32 v[64:65], v[202:203], v[182:183]
	v_pk_mul_f32 v[66:67], v[204:205], v[184:185]
	v_mul_f32_e32 v64, v64, v65
	v_mul_f32_e32 v65, v66, v67
	v_cvt_pk_bf16_f32 v64, v186, v64
	v_cvt_pk_bf16_f32 v65, v187, v65
	global_store_dwordx2 v[68:69], v[64:65], off offset:32 sc1
	v_mov_b64_e32 v[64:65], v[224:225]
	v_mov_b64_e32 v[66:67], v[226:227]
	v_lshlrev_b32_e32 v182, 16, v62
	v_lshlrev_b32_e32 v184, 16, v63
	v_mul_f32_e32 v183, 0xbfb8aa3b, v182
	v_mul_f32_e32 v185, 0xbfb8aa3b, v184
	v_exp_f32_e32 v183, v183
	v_exp_f32_e32 v185, v185
	v_mov_b32_e32 v187, v210
	v_mov_b32_e32 v189, v212
	v_add_f32_e32 v183, 1.0, v183
	v_add_f32_e32 v185, 1.0, v185
	v_rcp_f32_e32 v186, v183
	v_rcp_f32_e32 v188, v185
	v_mov_b32_e32 v183, v64
	v_and_b32_e32 v64, 0xffff0000, v62
	v_mov_b32_e32 v185, v66
	v_and_b32_e32 v66, 0xffff0000, v63
	v_mul_f32_e32 v62, 0xbfb8aa3b, v64
	v_mul_f32_e32 v63, 0xbfb8aa3b, v66
	v_exp_f32_e32 v190, v62
	v_exp_f32_e32 v191, v63
	v_pk_mul_f32 v[62:63], v[186:187], v[182:183]
	v_pk_mul_f32 v[182:183], v[188:189], v[184:185]
	v_add_f32_e32 v184, 1.0, v190
	v_add_f32_e32 v185, 1.0, v191
	v_rcp_f32_e32 v210, v184
	v_rcp_f32_e32 v212, v185
	v_mul_f32_e32 v184, v62, v63
	v_mul_f32_e32 v182, v182, v183
	v_pk_mul_f32 v[62:63], v[210:211], v[64:65]
	v_pk_mul_f32 v[64:65], v[212:213], v[66:67]
	v_mul_f32_e32 v62, v62, v63
	v_mul_f32_e32 v63, v64, v65
	v_cvt_pk_bf16_f32 v62, v184, v62
	v_cvt_pk_bf16_f32 v63, v182, v63
	global_store_dwordx2 v[68:69], v[62:63], off offset:64 sc1
	v_mov_b64_e32 v[62:63], v[228:229]
	v_mov_b64_e32 v[64:65], v[230:231]
	v_lshlrev_b32_e32 v66, 16, v60
	v_lshlrev_b32_e32 v182, 16, v61
	v_mul_f32_e32 v67, 0xbfb8aa3b, v66
	v_mul_f32_e32 v183, 0xbfb8aa3b, v182
	v_exp_f32_e32 v67, v67
	v_exp_f32_e32 v183, v183
	v_mov_b32_e32 v185, v36
	v_mov_b32_e32 v187, v38
	v_add_f32_e32 v36, 1.0, v67
	v_add_f32_e32 v38, 1.0, v183
	v_rcp_f32_e32 v184, v36
	v_rcp_f32_e32 v186, v38
	v_mov_b32_e32 v67, v62
	v_and_b32_e32 v62, 0xffff0000, v60
	v_mov_b32_e32 v183, v64
	v_and_b32_e32 v64, 0xffff0000, v61
	v_mul_f32_e32 v36, 0xbfb8aa3b, v62
	v_mul_f32_e32 v38, 0xbfb8aa3b, v64
	v_exp_f32_e32 v36, v36
	v_exp_f32_e32 v38, v38
	v_pk_mul_f32 v[60:61], v[184:185], v[66:67]
	v_pk_mul_f32 v[66:67], v[186:187], v[182:183]
	v_add_f32_e32 v36, 1.0, v36
	v_add_f32_e32 v38, 1.0, v38
	v_rcp_f32_e32 v36, v36
	v_rcp_f32_e32 v38, v38
	v_mul_f32_e32 v60, v60, v61
	v_mul_f32_e32 v61, v66, v67
	v_pk_mul_f32 v[36:37], v[36:37], v[62:63]
	v_pk_mul_f32 v[38:39], v[38:39], v[64:65]
; __device__ __forceinline__ unsigned cvt_pk(float lo, float hi) { unsigned r; asm volatile("v_cvt_pk_bf16_f32 %0, %1, %2" : "=v"(r) : "v"(lo), "v"(hi)); return r; }
; __device__ __forceinline__ float bflo(unsigned w) { return __uint_as_float(w << 16); }
; __device__ __forceinline__ float bfhi(unsigned w) { return __uint_as_float(w & 0xffff0000u); }
; __device__ __forceinline__ float silu(float x) { return x * sigm(x); }
; __device__ void phase_mix(const Params& p, unsigned char* smem) {
;     ...
; #pragma unroll
;             for (int nb = 0; nb < 8; ++nb) { const int d = nb * 16 + kq * 4;
;                 const u32x2 za = zreg[nb]; const f32x4 ps = *(const f32x4*)(p.pool_scale + g * 128 + d);
;                 u32x2 o; o.x = cvt_pk(acc[nb][0] * ps[0] * silu(bflo(za.x)), acc[nb][1] * ps[1] * silu(bfhi(za.x)));
;                 o.y = cvt_pk(acc[nb][2] * ps[2] * silu(bflo(za.y)), acc[nb][3] * ps[3] * silu(bfhi(za.y)));
;                 *(u32x2*)(CAT0 + r * 1024 + g * 128 + d) = o; }
;         }
	v_mul_f32_e32 v36, v36, v37
	v_mul_f32_e32 v37, v38, v39
	v_cvt_pk_bf16_f32 v36, v60, v36
	v_cvt_pk_bf16_f32 v37, v61, v37
	global_store_dwordx2 v[68:69], v[36:37], off offset:96 sc1
	v_mov_b64_e32 v[36:37], v[232:233]
	v_mov_b64_e32 v[38:39], v[234:235]
	v_lshlrev_b32_e32 v60, 16, v58
	v_lshlrev_b32_e32 v62, 16, v59
	v_mul_f32_e32 v61, 0xbfb8aa3b, v60
	v_mul_f32_e32 v63, 0xbfb8aa3b, v62
	v_exp_f32_e32 v61, v61
	v_exp_f32_e32 v63, v63
	v_mov_b32_e32 v65, v32
	v_mov_b32_e32 v67, v34
	v_add_f32_e32 v32, 1.0, v61
	v_add_f32_e32 v34, 1.0, v63
	v_rcp_f32_e32 v64, v32
	v_rcp_f32_e32 v66, v34
	v_mov_b32_e32 v61, v36
	v_and_b32_e32 v36, 0xffff0000, v58
	v_mov_b32_e32 v63, v38
	v_and_b32_e32 v38, 0xffff0000, v59
	v_mul_f32_e32 v32, 0xbfb8aa3b, v36
	v_mul_f32_e32 v34, 0xbfb8aa3b, v38
	v_exp_f32_e32 v32, v32
	v_exp_f32_e32 v34, v34
	v_pk_mul_f32 v[58:59], v[64:65], v[60:61]
	v_pk_mul_f32 v[60:61], v[66:67], v[62:63]
	v_add_f32_e32 v32, 1.0, v32
	v_add_f32_e32 v34, 1.0, v34
	v_rcp_f32_e32 v32, v32
	v_rcp_f32_e32 v34, v34
	v_mul_f32_e32 v58, v58, v59
	v_mul_f32_e32 v59, v60, v61
	v_pk_mul_f32 v[32:33], v[32:33], v[36:37]
	v_pk_mul_f32 v[34:35], v[34:35], v[38:39]
	v_mul_f32_e32 v32, v32, v33
	v_mul_f32_e32 v33, v34, v35
	v_cvt_pk_bf16_f32 v32, v58, v32
	v_cvt_pk_bf16_f32 v33, v59, v33
	global_store_dwordx2 v[68:69], v[32:33], off offset:128 sc1
	v_mov_b64_e32 v[32:33], v[236:237]
	v_mov_b64_e32 v[34:35], v[238:239]
	v_lshlrev_b32_e32 v36, 16, v56
	v_lshlrev_b32_e32 v38, 16, v57
	v_mul_f32_e32 v37, 0xbfb8aa3b, v36
	v_mul_f32_e32 v39, 0xbfb8aa3b, v38
	v_exp_f32_e32 v37, v37
	v_exp_f32_e32 v39, v39
	v_mov_b32_e32 v59, v28
	v_mov_b32_e32 v61, v30
	v_add_f32_e32 v28, 1.0, v37
	v_add_f32_e32 v30, 1.0, v39
	v_rcp_f32_e32 v58, v28
	v_rcp_f32_e32 v60, v30
	v_mov_b32_e32 v37, v32
	v_and_b32_e32 v32, 0xffff0000, v56
	v_mov_b32_e32 v39, v34
	v_and_b32_e32 v34, 0xffff0000, v57
	v_mul_f32_e32 v28, 0xbfb8aa3b, v32
	v_mul_f32_e32 v30, 0xbfb8aa3b, v34
	v_exp_f32_e32 v28, v28
	v_exp_f32_e32 v30, v30
	v_pk_mul_f32 v[36:37], v[58:59], v[36:37]
	v_pk_mul_f32 v[38:39], v[60:61], v[38:39]
	v_add_f32_e32 v28, 1.0, v28
	v_add_f32_e32 v30, 1.0, v30
	v_rcp_f32_e32 v28, v28
	v_rcp_f32_e32 v30, v30
	v_mul_f32_e32 v36, v36, v37
	v_mul_f32_e32 v37, v38, v39
	v_pk_mul_f32 v[28:29], v[28:29], v[32:33]
	v_pk_mul_f32 v[30:31], v[30:31], v[34:35]
	v_mul_f32_e32 v28, v28, v29
	v_mul_f32_e32 v29, v30, v31
	v_cvt_pk_bf16_f32 v28, v36, v28
	v_cvt_pk_bf16_f32 v29, v37, v29
	global_store_dwordx2 v[68:69], v[28:29], off offset:160 sc1
	v_mov_b64_e32 v[28:29], v[240:241]
	v_mov_b64_e32 v[30:31], v[242:243]
	v_lshlrev_b32_e32 v32, 16, v54
	v_lshlrev_b32_e32 v34, 16, v55
	v_mul_f32_e32 v33, 0xbfb8aa3b, v32
	v_mul_f32_e32 v35, 0xbfb8aa3b, v34
	v_exp_f32_e32 v33, v33
	v_exp_f32_e32 v35, v35
	v_mov_b32_e32 v37, v24
	v_mov_b32_e32 v39, v26
	v_add_f32_e32 v24, 1.0, v33
	v_add_f32_e32 v26, 1.0, v35
	v_rcp_f32_e32 v36, v24
	v_rcp_f32_e32 v38, v26
	v_mov_b32_e32 v33, v28
	v_and_b32_e32 v28, 0xffff0000, v54
	v_mov_b32_e32 v35, v30
	v_and_b32_e32 v30, 0xffff0000, v55
	v_mul_f32_e32 v24, 0xbfb8aa3b, v28
	v_mul_f32_e32 v26, 0xbfb8aa3b, v30
	v_exp_f32_e32 v24, v24
	v_exp_f32_e32 v26, v26
	v_pk_mul_f32 v[32:33], v[36:37], v[32:33]
	v_pk_mul_f32 v[34:35], v[38:39], v[34:35]
	v_add_f32_e32 v24, 1.0, v24
	v_add_f32_e32 v26, 1.0, v26
	v_rcp_f32_e32 v24, v24
	v_rcp_f32_e32 v26, v26
	v_mul_f32_e32 v32, v32, v33
	v_mul_f32_e32 v33, v34, v35
	v_pk_mul_f32 v[24:25], v[24:25], v[28:29]
	v_pk_mul_f32 v[26:27], v[26:27], v[30:31]
	v_mul_f32_e32 v24, v24, v25
	v_mul_f32_e32 v25, v26, v27
	v_cvt_pk_bf16_f32 v24, v32, v24
	v_cvt_pk_bf16_f32 v25, v33, v25
	global_store_dwordx2 v[68:69], v[24:25], off offset:192 sc1
	v_mov_b64_e32 v[24:25], v[244:245]
	v_mov_b64_e32 v[26:27], v[246:247]
	v_lshlrev_b32_e32 v28, 16, v52
	v_lshlrev_b32_e32 v32, 16, v53
	v_mov_b32_e32 v31, v20
	v_mov_b32_e32 v35, v22
	v_mul_f32_e32 v20, 0xbfb8aa3b, v28
	v_mul_f32_e32 v22, 0xbfb8aa3b, v32
	v_exp_f32_e32 v20, v20
	v_exp_f32_e32 v22, v22
	v_add_f32_e32 v20, 1.0, v20
	v_add_f32_e32 v22, 1.0, v22
	v_rcp_f32_e32 v30, v20
	v_rcp_f32_e32 v34, v22
	v_mov_b32_e32 v29, v24
	v_and_b32_e32 v24, 0xffff0000, v52
	v_mov_b32_e32 v33, v26
	v_and_b32_e32 v26, 0xffff0000, v53
	v_mul_f32_e32 v20, 0xbfb8aa3b, v24
	v_mul_f32_e32 v22, 0xbfb8aa3b, v26
	v_exp_f32_e32 v20, v20
	v_exp_f32_e32 v22, v22
	v_pk_mul_f32 v[28:29], v[30:31], v[28:29]
	v_pk_mul_f32 v[30:31], v[34:35], v[32:33]
	v_add_f32_e32 v20, 1.0, v20
	v_add_f32_e32 v22, 1.0, v22
	v_rcp_f32_e32 v20, v20
	v_rcp_f32_e32 v22, v22
	v_mul_f32_e32 v28, v28, v29
	v_mul_f32_e32 v29, v30, v31
	v_pk_mul_f32 v[20:21], v[20:21], v[24:25]
	v_pk_mul_f32 v[22:23], v[22:23], v[26:27]
	v_mul_f32_e32 v20, v20, v21
	v_mul_f32_e32 v21, v22, v23
	v_cvt_pk_bf16_f32 v20, v28, v20
	v_cvt_pk_bf16_f32 v21, v29, v21
	global_store_dwordx2 v[68:69], v[20:21], off offset:224 sc1
	s_cbranch_vccnz .LBB0_169

; __device__ __forceinline__ unsigned cvt_pk(float lo, float hi) { unsigned r; asm volatile("v_cvt_pk_bf16_f32 %0, %1, %2" : "=v"(r) : "v"(lo), "v"(hi)); return r; }
; __device__ void phase_mix(const Params& p, unsigned char* smem) {
;     ...
;             bf16x8 af[4]; ldfrag(af, As, wid, lane);
;             const size_t r = (size_t)r0 + wid * 16 + li;
; #pragma unroll
;             for (int which = 0; which < 2; ++which) {
;                 f32x4 acc[8];
; #pragma unroll
;                 for (int nb = 0; nb < 8; ++nb) acc[nb] = (f32x4){0.f, 0.f, 0.f, 0.f};
;                 mm16<8>(acc, which ? B2s : Bs, af, lane);
;                 bf16_t* O = which ? K0 : Q0;
; #pragma unroll
;                 for (int nb = 0; nb < 8; ++nb) { u32x2 o; o.x = cvt_pk(acc[nb][0], acc[nb][1]); o.y = cvt_pk(acc[nb][2], acc[nb][3]);
;                     *(u32x2*)(O + r * 512 + h * 128 + nb * 16 + kq * 4) = o; }
;             }
.LBB0_199:
	s_or_b64 exec, exec, s[6:7]
	v_add_u32_e32 v158, v108, v104
	ds_read_b128 v[80:83], v158 offset:32768
	ds_read_b128 v[118:121], v158 offset:36864
	ds_read_b128 v[122:125], v114
	ds_read_b128 v[126:129], v115
	ds_read_b128 v[134:137], v158 offset:40960
	v_lshl_add_u64 v[102:103], v[94:95], 0, s[0:1]
	v_lshlrev_b64 v[102:103], 10, v[102:103]
	s_waitcnt lgkmcnt(2)
	v_mfma_f32_16x16x32_bf16 v[130:133], v[80:83], v[122:125], 0
	ds_read_b128 v[138:141], v158 offset:45056
	ds_read_b128 v[142:145], v116
	ds_read_b128 v[80:83], v117
	v_lshl_add_u64 v[102:103], v[96:97], 0, v[102:103]
	v_mfma_f32_16x16x32_bf16 v[118:121], v[118:121], v[122:125], 0
	s_waitcnt lgkmcnt(3)
	v_mfma_f32_16x16x32_bf16 v[134:137], v[134:137], v[122:125], 0
	s_waitcnt lgkmcnt(2)
	v_mfma_f32_16x16x32_bf16 v[138:141], v[138:141], v[122:125], 0
	ds_read_b128 v[146:149], v158 offset:49152
	ds_read_b128 v[150:153], v158 offset:53248
	ds_read_b128 v[154:157], v158 offset:57344
	ds_read_b128 v[158:161], v158 offset:61440
	s_waitcnt lgkmcnt(3)
	v_mfma_f32_16x16x32_bf16 v[146:149], v[146:149], v[122:125], 0
	s_waitcnt lgkmcnt(2)
	v_mfma_f32_16x16x32_bf16 v[150:153], v[150:153], v[122:125], 0
	s_waitcnt lgkmcnt(1)
	v_mfma_f32_16x16x32_bf16 v[154:157], v[154:157], v[122:125], 0
	s_waitcnt lgkmcnt(0)
	v_mfma_f32_16x16x32_bf16 v[158:161], v[158:161], v[122:125], 0
	v_add_u32_e32 v171, v108, v105
	ds_read_b128 v[162:165], v171 offset:32768
	ds_read_b128 v[166:169], v171 offset:36864
	s_waitcnt lgkmcnt(1)
	v_mfma_f32_16x16x32_bf16 v[130:133], v[162:165], v[126:129], v[130:133]
	ds_read_b128 v[162:165], v171 offset:40960
	s_waitcnt lgkmcnt(1)
	v_mfma_f32_16x16x32_bf16 v[118:121], v[166:169], v[126:129], v[118:121]
	ds_read_b128 v[166:169], v171 offset:45056
	s_waitcnt lgkmcnt(1)
	v_mfma_f32_16x16x32_bf16 v[134:137], v[162:165], v[126:129], v[134:137]
	s_waitcnt lgkmcnt(0)
	v_mfma_f32_16x16x32_bf16 v[138:141], v[166:169], v[126:129], v[138:141]
	ds_read_b128 v[162:165], v171 offset:49152
	ds_read_b128 v[166:169], v171 offset:53248
	s_waitcnt lgkmcnt(1)
	v_mfma_f32_16x16x32_bf16 v[146:149], v[162:165], v[126:129], v[146:149]
	ds_read_b128 v[162:165], v171 offset:57344
	s_waitcnt lgkmcnt(1)
	v_mfma_f32_16x16x32_bf16 v[150:153], v[166:169], v[126:129], v[150:153]
	ds_read_b128 v[166:169], v171 offset:61440
	s_waitcnt lgkmcnt(1)
	v_mfma_f32_16x16x32_bf16 v[154:157], v[162:165], v[126:129], v[154:157]
	s_waitcnt lgkmcnt(0)
	v_mfma_f32_16x16x32_bf16 v[158:161], v[166:169], v[126:129], v[158:161]
	v_add_u32_e32 v171, v108, v106
	ds_read_b128 v[162:165], v171 offset:32768
	ds_read_b128 v[166:169], v171 offset:36864
	s_waitcnt lgkmcnt(1)
	v_mfma_f32_16x16x32_bf16 v[130:133], v[162:165], v[142:145], v[130:133]
	ds_read_b128 v[162:165], v171 offset:40960
	s_waitcnt lgkmcnt(1)
	v_mfma_f32_16x16x32_bf16 v[118:121], v[166:169], v[142:145], v[118:121]
	ds_read_b128 v[166:169], v171 offset:45056
	s_waitcnt lgkmcnt(1)
	v_mfma_f32_16x16x32_bf16 v[134:137], v[162:165], v[142:145], v[134:137]
	s_waitcnt lgkmcnt(0)
	v_mfma_f32_16x16x32_bf16 v[138:141], v[166:169], v[142:145], v[138:141]
	ds_read_b128 v[162:165], v171 offset:49152
	ds_read_b128 v[166:169], v171 offset:53248
	s_waitcnt lgkmcnt(1)
	v_mfma_f32_16x16x32_bf16 v[146:149], v[162:165], v[142:145], v[146:149]
	ds_read_b128 v[162:165], v171 offset:57344
	s_waitcnt lgkmcnt(1)
	v_mfma_f32_16x16x32_bf16 v[150:153], v[166:169], v[142:145], v[150:153]
	ds_read_b128 v[166:169], v171 offset:61440
	s_waitcnt lgkmcnt(1)
	v_mfma_f32_16x16x32_bf16 v[154:157], v[162:165], v[142:145], v[154:157]
	s_waitcnt lgkmcnt(0)
	v_mfma_f32_16x16x32_bf16 v[158:161], v[166:169], v[142:145], v[158:161]
	v_add_u32_e32 v171, v108, v107
	ds_read_b128 v[162:165], v171 offset:32768
	ds_read_b128 v[166:169], v171 offset:36864
	s_waitcnt lgkmcnt(1)
	v_mfma_f32_16x16x32_bf16 v[130:133], v[162:165], v[80:83], v[130:133]
	ds_read_b128 v[162:165], v171 offset:40960
	s_waitcnt lgkmcnt(1)
	v_mfma_f32_16x16x32_bf16 v[118:121], v[166:169], v[80:83], v[118:121]
	ds_read_b128 v[166:169], v171 offset:45056
	s_waitcnt lgkmcnt(1)
	v_mfma_f32_16x16x32_bf16 v[134:137], v[162:165], v[80:83], v[134:137]
	s_waitcnt lgkmcnt(0)
	v_mfma_f32_16x16x32_bf16 v[138:141], v[166:169], v[80:83], v[138:141]
	ds_read_b128 v[162:165], v171 offset:49152
	ds_read_b128 v[166:169], v171 offset:53248
	s_waitcnt lgkmcnt(1)
	v_mfma_f32_16x16x32_bf16 v[146:149], v[162:165], v[80:83], v[146:149]
	ds_read_b128 v[162:165], v171 offset:57344
	s_waitcnt lgkmcnt(1)
	v_mfma_f32_16x16x32_bf16 v[150:153], v[166:169], v[80:83], v[150:153]
	ds_read_b128 v[166:169], v171 offset:61440
	s_waitcnt lgkmcnt(1)
	v_mfma_f32_16x16x32_bf16 v[154:157], v[162:165], v[80:83], v[154:157]
	s_waitcnt lgkmcnt(0)
	v_mfma_f32_16x16x32_bf16 v[158:161], v[166:169], v[80:83], v[158:161]
	v_cvt_pk_bf16_f32 v130, v130, v131
	v_cvt_pk_bf16_f32 v131, v132, v133
	global_store_dwordx2 v[102:103], v[130:131], off sc1
	v_cvt_pk_bf16_f32 v118, v118, v119
	v_cvt_pk_bf16_f32 v119, v120, v121
	global_store_dwordx2 v[102:103], v[118:119], off offset:32 sc1
	v_cvt_pk_bf16_f32 v118, v134, v135
	v_cvt_pk_bf16_f32 v119, v136, v137
	global_store_dwordx2 v[102:103], v[118:119], off offset:64 sc1
	v_cvt_pk_bf16_f32 v118, v138, v139
	v_cvt_pk_bf16_f32 v119, v140, v141
	global_store_dwordx2 v[102:103], v[118:119], off offset:96 sc1
	v_cvt_pk_bf16_f32 v118, v146, v147
	v_cvt_pk_bf16_f32 v119, v148, v149
	global_store_dwordx2 v[102:103], v[118:119], off offset:128 sc1
	v_cvt_pk_bf16_f32 v118, v150, v151
	v_cvt_pk_bf16_f32 v119, v152, v153
	global_store_dwordx2 v[102:103], v[118:119], off offset:160 sc1
	v_cvt_pk_bf16_f32 v118, v154, v155
	v_cvt_pk_bf16_f32 v119, v156, v157
	global_store_dwordx2 v[102:103], v[118:119], off offset:192 sc1
	v_cvt_pk_bf16_f32 v146, v158, v159
	s_nop 0
	v_add_u32_e32 v158, v109, v104
	v_cvt_pk_bf16_f32 v147, v160, v161
	ds_read_b128 v[118:121], v158
	ds_read_b128 v[130:133], v158 offset:4096
	ds_read_b128 v[134:137], v158 offset:8192
	ds_read_b128 v[138:141], v158 offset:12288
	s_waitcnt lgkmcnt(3)
; __device__ __forceinline__ unsigned cvt_pk(float lo, float hi) { unsigned r; asm volatile("v_cvt_pk_bf16_f32 %0, %1, %2" : "=v"(r) : "v"(lo), "v"(hi)); return r; }
; __device__ void phase_mix(const Params& p, unsigned char* smem) {
;     ...
;             for (int which = 0; which < 2; ++which) {
;                 f32x4 acc[8];
; #pragma unroll
;                 for (int nb = 0; nb < 8; ++nb) acc[nb] = (f32x4){0.f, 0.f, 0.f, 0.f};
;                 mm16<8>(acc, which ? B2s : Bs, af, lane);
;                 bf16_t* O = which ? K0 : Q0;
; #pragma unroll
;                 for (int nb = 0; nb < 8; ++nb) { u32x2 o; o.x = cvt_pk(acc[nb][0], acc[nb][1]); o.y = cvt_pk(acc[nb][2], acc[nb][3]);
;                     *(u32x2*)(O + r * 512 + h * 128 + nb * 16 + kq * 4) = o; }
;             }
;             __syncthreads();
	v_mfma_f32_16x16x32_bf16 v[118:121], v[118:121], v[122:125], 0
	global_store_dwordx2 v[102:103], v[146:147], off offset:224 sc1
	s_waitcnt lgkmcnt(2)
	v_mfma_f32_16x16x32_bf16 v[130:133], v[130:133], v[122:125], 0
	s_waitcnt lgkmcnt(1)
	v_mfma_f32_16x16x32_bf16 v[134:137], v[134:137], v[122:125], 0
	s_waitcnt lgkmcnt(0)
	v_mfma_f32_16x16x32_bf16 v[138:141], v[138:141], v[122:125], 0
	ds_read_b128 v[146:149], v158 offset:16384
	ds_read_b128 v[150:153], v158 offset:20480
	ds_read_b128 v[154:157], v158 offset:24576
	ds_read_b128 v[158:161], v158 offset:28672
	s_waitcnt lgkmcnt(3)
	v_mfma_f32_16x16x32_bf16 v[146:149], v[146:149], v[122:125], 0
	s_waitcnt lgkmcnt(2)
	v_mfma_f32_16x16x32_bf16 v[150:153], v[150:153], v[122:125], 0
	s_waitcnt lgkmcnt(1)
	v_mfma_f32_16x16x32_bf16 v[154:157], v[154:157], v[122:125], 0
	s_waitcnt lgkmcnt(0)
	v_mfma_f32_16x16x32_bf16 v[122:125], v[158:161], v[122:125], 0
	v_add_u32_e32 v166, v109, v105
	ds_read_b128 v[158:161], v166
	ds_read_b128 v[162:165], v166 offset:4096
	s_waitcnt lgkmcnt(1)
	v_mfma_f32_16x16x32_bf16 v[118:121], v[158:161], v[126:129], v[118:121]
	ds_read_b128 v[158:161], v166 offset:8192
	s_waitcnt lgkmcnt(1)
	v_mfma_f32_16x16x32_bf16 v[130:133], v[162:165], v[126:129], v[130:133]
	ds_read_b128 v[162:165], v166 offset:12288
	s_waitcnt lgkmcnt(1)
	v_mfma_f32_16x16x32_bf16 v[134:137], v[158:161], v[126:129], v[134:137]
	s_waitcnt lgkmcnt(0)
	v_mfma_f32_16x16x32_bf16 v[138:141], v[162:165], v[126:129], v[138:141]
	ds_read_b128 v[158:161], v166 offset:16384
	ds_read_b128 v[162:165], v166 offset:20480
	s_waitcnt lgkmcnt(1)
	v_mfma_f32_16x16x32_bf16 v[146:149], v[158:161], v[126:129], v[146:149]
	ds_read_b128 v[158:161], v166 offset:24576
	s_waitcnt lgkmcnt(1)
	v_mfma_f32_16x16x32_bf16 v[150:153], v[162:165], v[126:129], v[150:153]
	ds_read_b128 v[162:165], v166 offset:28672
	s_waitcnt lgkmcnt(1)
	v_mfma_f32_16x16x32_bf16 v[154:157], v[158:161], v[126:129], v[154:157]
	s_waitcnt lgkmcnt(0)
	v_mfma_f32_16x16x32_bf16 v[122:125], v[162:165], v[126:129], v[122:125]
	v_add_u32_e32 v162, v109, v106
	ds_read_b128 v[126:129], v162
	ds_read_b128 v[158:161], v162 offset:4096
	s_waitcnt lgkmcnt(1)
	v_mfma_f32_16x16x32_bf16 v[118:121], v[126:129], v[142:145], v[118:121]
	ds_read_b128 v[126:129], v162 offset:8192
	s_waitcnt lgkmcnt(1)
	v_mfma_f32_16x16x32_bf16 v[130:133], v[158:161], v[142:145], v[130:133]
	ds_read_b128 v[158:161], v162 offset:12288
	s_waitcnt lgkmcnt(1)
	v_mfma_f32_16x16x32_bf16 v[126:129], v[126:129], v[142:145], v[134:137]
	s_waitcnt lgkmcnt(0)
	v_mfma_f32_16x16x32_bf16 v[134:137], v[158:161], v[142:145], v[138:141]
	s_nop 2
	ds_read_b128 v[138:141], v162 offset:16384
	ds_read_b128 v[158:161], v162 offset:20480
	s_waitcnt lgkmcnt(1)
	v_mfma_f32_16x16x32_bf16 v[138:141], v[138:141], v[142:145], v[146:149]
	s_nop 2
	ds_read_b128 v[146:149], v162 offset:24576
	s_waitcnt lgkmcnt(1)
	v_mfma_f32_16x16x32_bf16 v[150:153], v[158:161], v[142:145], v[150:153]
	ds_read_b128 v[158:161], v162 offset:28672
	s_waitcnt lgkmcnt(1)
	v_mfma_f32_16x16x32_bf16 v[146:149], v[146:149], v[142:145], v[154:157]
	s_waitcnt lgkmcnt(0)
	v_mfma_f32_16x16x32_bf16 v[122:125], v[158:161], v[142:145], v[122:125]
	v_add_u32_e32 v158, v109, v107
	ds_read_b128 v[142:145], v158
	ds_read_b128 v[154:157], v158 offset:4096
	s_waitcnt lgkmcnt(1)
	v_mfma_f32_16x16x32_bf16 v[118:121], v[142:145], v[80:83], v[118:121]
	ds_read_b128 v[142:145], v158 offset:8192
	s_waitcnt lgkmcnt(1)
	v_mfma_f32_16x16x32_bf16 v[130:133], v[154:157], v[80:83], v[130:133]
	ds_read_b128 v[154:157], v158 offset:12288
	s_waitcnt lgkmcnt(1)
	v_mfma_f32_16x16x32_bf16 v[126:129], v[142:145], v[80:83], v[126:129]
	s_waitcnt lgkmcnt(0)
	v_mfma_f32_16x16x32_bf16 v[134:137], v[154:157], v[80:83], v[134:137]
	ds_read_b128 v[142:145], v158 offset:16384
	ds_read_b128 v[154:157], v158 offset:20480
	s_waitcnt lgkmcnt(1)
	v_mfma_f32_16x16x32_bf16 v[138:141], v[142:145], v[80:83], v[138:141]
	ds_read_b128 v[142:145], v158 offset:24576
	s_waitcnt lgkmcnt(1)
	v_mfma_f32_16x16x32_bf16 v[150:153], v[154:157], v[80:83], v[150:153]
	ds_read_b128 v[154:157], v158 offset:28672
	s_waitcnt lgkmcnt(1)
	v_mfma_f32_16x16x32_bf16 v[142:145], v[142:145], v[80:83], v[146:149]
	s_waitcnt lgkmcnt(0)
	v_mfma_f32_16x16x32_bf16 v[80:83], v[154:157], v[80:83], v[122:125]
	v_add_co_u32_e32 v102, vcc, s14, v102
	v_cvt_pk_bf16_f32 v118, v118, v119
	v_cvt_pk_bf16_f32 v119, v120, v121
	s_add_i32 s0, s0, s10
	s_nop 0
	v_addc_co_u32_e32 v103, vcc, 0, v103, vcc
	global_store_dwordx2 v[102:103], v[118:119], off sc1
	v_cvt_pk_bf16_f32 v118, v130, v131
	v_cvt_pk_bf16_f32 v119, v132, v133
	global_store_dwordx2 v[102:103], v[118:119], off offset:32 sc1
	v_cvt_pk_bf16_f32 v118, v126, v127
	v_cvt_pk_bf16_f32 v119, v128, v129
	global_store_dwordx2 v[102:103], v[118:119], off offset:64 sc1
	v_cvt_pk_bf16_f32 v118, v134, v135
	v_cvt_pk_bf16_f32 v119, v136, v137
	global_store_dwordx2 v[102:103], v[118:119], off offset:96 sc1
	v_cvt_pk_bf16_f32 v118, v138, v139
	v_cvt_pk_bf16_f32 v119, v140, v141
	global_store_dwordx2 v[102:103], v[118:119], off offset:128 sc1
	v_cvt_pk_bf16_f32 v118, v150, v151
	v_cvt_pk_bf16_f32 v119, v152, v153
	s_andn2_b64 vcc, exec, s[4:5]
	global_store_dwordx2 v[102:103], v[118:119], off offset:160 sc1
	v_cvt_pk_bf16_f32 v118, v142, v143
	v_cvt_pk_bf16_f32 v119, v144, v145
	global_store_dwordx2 v[102:103], v[118:119], off offset:192 sc1
	v_cvt_pk_bf16_f32 v80, v80, v81
	v_cvt_pk_bf16_f32 v81, v82, v83
	global_store_dwordx2 v[102:103], v[80:81], off offset:224 sc1
	s_barrier
	s_cbranch_vccz .LBB0_224
; __device__ __forceinline__ unsigned cvt_pk(float lo, float hi) { unsigned r; asm volatile("v_cvt_pk_bf16_f32 %0, %1, %2" : "=v"(r) : "v"(lo), "v"(hi)); return r; }
; __device__ __forceinline__ float bflo(unsigned w) { return __uint_as_float(w << 16); }
; __device__ __forceinline__ float bfhi(unsigned w) { return __uint_as_float(w & 0xffff0000u); }
; __device__ __forceinline__ float silu(float x) { return x * sigm(x); }
; #define TILE_DECODE(tile_) const int tile = (tile_) & 511; const int r0 = tile * 128; int T, ts0; \
;         if (r0 < NPROMPT) { T = 4096; ts0 = r0 & 4095; } else { T = 2048; ts0 = (r0 - NPROMPT) & 2047; }
; __device__ void phase_mix(const Params& p, unsigned char* smem) {
;     ...
;         for (int tile_ = blockIdx.x >> 2; tile_ < tlim; tile_ += tstep) {
;             TILE_DECODE(tile_); (void)T; (void)ts0;
; #pragma unroll
;             for (int i = 0; i < 4; ++i) { const int tl = (tid >> 4) + 32 * i; const size_t r = (size_t)r0 + tl;
;                 float a[8];
; #pragma unroll
;                 for (int e = 0; e < 8; ++e) a[e] = cb[e];
; #pragma unroll
;                 for (int j = 0; j < 3; ++j) { const u32x4 v = creg[i][j];
;                     a[0] += bflo(v.x) * cw[j][0]; a[1] += bfhi(v.x) * cw[j][1]; a[2] += bflo(v.y) * cw[j][2]; a[3] += bfhi(v.y) * cw[j][3];
;                     a[4] += bflo(v.z) * cw[j][4]; a[5] += bfhi(v.z) * cw[j][5]; a[6] += bflo(v.w) * cw[j][6]; a[7] += bfhi(v.w) * cw[j][7]; }
;                 u32x4 w; w.x = cvt_pk(silu(a[0]), silu(a[1])); w.y = cvt_pk(silu(a[2]), silu(a[3])); w.z = cvt_pk(silu(a[4]), silu(a[5])); w.w = cvt_pk(silu(a[6]), silu(a[7]));
;                 *(u32x4*)(As + swz(tl, ch)) = w; *(u32x4*)(CAT0 + r * 1024 + 512 + cc) = w; }
;             __syncthreads();
;             CLOAD((tile_ + tstep < tlim) ? tile_ + tstep : tile_);
.LBB0_200:
	s_waitcnt vmcnt(16)
	v_lshlrev_b32_e32 v80, 16, v36
	v_and_b32_e32 v36, 0xffff0000, v36
	v_fma_f32 v81, v13, v36, v9
	v_lshlrev_b32_e32 v36, 16, v37
	v_fma_f32 v82, v14, v36, v10
	v_and_b32_e32 v36, 0xffff0000, v37
	v_fma_f32 v83, v15, v36, v11
	v_lshlrev_b32_e32 v36, 16, v38
	v_fma_f32 v102, v4, v36, v0
	v_and_b32_e32 v36, 0xffff0000, v38
	v_fma_f32 v38, v5, v36, v1
	v_lshlrev_b32_e32 v36, 16, v39
	v_fma_f32 v103, v6, v36, v2
	v_and_b32_e32 v36, 0xffff0000, v39
	v_fma_f32 v39, v7, v36, v3
	v_lshlrev_b32_e32 v37, 16, v32
	v_lshlrev_b32_e32 v36, 16, v48
	v_fma_f32 v80, v12, v80, v8
	v_pk_mul_f32 v[36:37], v[24:25], v[36:37]
	s_mov_b32 s6, s24
	v_add_f32_e32 v37, v37, v80
	v_add_f32_e32 v80, v36, v37
	v_and_b32_e32 v37, 0xffff0000, v32
	v_and_b32_e32 v36, 0xffff0000, v48
	v_pk_mul_f32 v[36:37], v[20:21], v[36:37]
	s_add_i32 s24, s24, s3
	v_add_f32_e32 v32, v37, v81
	v_add_f32_e32 v48, v36, v32
	v_lshlrev_b32_e32 v36, 16, v49
	v_lshlrev_b32_e32 v37, 16, v33
	v_pk_mul_f32 v[36:37], v[26:27], v[36:37]
	v_and_b32_e32 v33, 0xffff0000, v33
	v_add_f32_e32 v32, v37, v82
	v_add_f32_e32 v81, v36, v32
	v_and_b32_e32 v32, 0xffff0000, v49
	v_pk_mul_f32 v[32:33], v[22:23], v[32:33]
	v_lshl_add_u64 v[36:37], s[0:1], 0, v[84:85]
	v_add_f32_e32 v33, v33, v83
	v_add_f32_e32 v49, v32, v33
	v_lshlrev_b32_e32 v33, 16, v34
	v_lshlrev_b32_e32 v32, 16, v50
	v_pk_mul_f32 v[32:33], v[28:29], v[32:33]
	v_lshlrev_b64 v[36:37], 11, v[36:37]
	v_add_f32_e32 v33, v33, v102
	v_add_f32_e32 v82, v32, v33
	v_and_b32_e32 v33, 0xffff0000, v34
	v_and_b32_e32 v32, 0xffff0000, v50
	v_pk_mul_f32 v[32:33], v[16:17], v[32:33]
	v_lshl_add_u64 v[36:37], v[98:99], 0, v[36:37]
	v_add_f32_e32 v33, v33, v38
	v_add_f32_e32 v34, v32, v33
	v_lshlrev_b32_e32 v32, 16, v51
	v_lshlrev_b32_e32 v33, 16, v35
	v_pk_mul_f32 v[32:33], v[30:31], v[32:33]
	v_mul_f32_e32 v50, 0xbfb8aa3b, v34
	v_add_f32_e32 v33, v33, v103
	v_add_f32_e32 v38, v32, v33
	v_and_b32_e32 v33, 0xffff0000, v35
	v_and_b32_e32 v32, 0xffff0000, v51
	v_pk_mul_f32 v[32:33], v[18:19], v[32:33]
	v_exp_f32_e32 v50, v50
	v_add_f32_e32 v33, v33, v39
	v_add_f32_e32 v35, v32, v33
	v_mul_f32_e32 v32, 0xbfb8aa3b, v80
	v_mul_f32_e32 v33, 0xbfb8aa3b, v48
	v_exp_f32_e32 v32, v32
	v_exp_f32_e32 v33, v33
	v_mul_f32_e32 v39, 0xbfb8aa3b, v81
	v_exp_f32_e32 v39, v39
	v_add_f32_e32 v32, 1.0, v32
	v_add_f32_e32 v33, 1.0, v33
	v_rcp_f32_e32 v32, v32
	v_rcp_f32_e32 v33, v33
	s_cmpk_gt_u32 s24, 0x1ff
	s_cselect_b64 s[4:5], -1, 0
	v_mul_f32_e32 v32, v80, v32
	v_mul_f32_e32 v33, v48, v33
	v_cvt_pk_bf16_f32 v32, v32, v33
	v_add_f32_e32 v33, 1.0, v39
	v_mul_f32_e32 v39, 0xbfb8aa3b, v49
	v_exp_f32_e32 v39, v39
	v_mul_f32_e32 v48, 0xbfb8aa3b, v82
	v_exp_f32_e32 v48, v48
	v_rcp_f32_e32 v33, v33
	v_add_f32_e32 v39, 1.0, v39
	v_rcp_f32_e32 v39, v39
	v_add_f32_e32 v48, 1.0, v48
	v_rcp_f32_e32 v48, v48
	v_mul_f32_e32 v33, v81, v33
	v_mul_f32_e32 v39, v49, v39
	v_cvt_pk_bf16_f32 v33, v33, v39
	v_mul_f32_e32 v39, v82, v48
	v_add_f32_e32 v48, 1.0, v50
	v_mul_f32_e32 v50, 0xbfb8aa3b, v35
	v_mul_f32_e32 v49, 0xbfb8aa3b, v38
	v_exp_f32_e32 v50, v50
	v_exp_f32_e32 v49, v49
	v_rcp_f32_e32 v48, v48
	s_cmpk_lt_u32 s24, 0x200
	v_add_f32_e32 v50, 1.0, v50
	v_add_f32_e32 v49, 1.0, v49
	v_rcp_f32_e32 v50, v50
	v_rcp_f32_e32 v49, v49
	v_mul_f32_e32 v34, v34, v48
	v_cvt_pk_bf16_f32 v34, v39, v34
	v_mul_f32_e32 v35, v35, v50
	v_mul_f32_e32 v38, v38, v49
	v_cvt_pk_bf16_f32 v35, v38, v35
	ds_write_b128 v110, v[32:35]
	global_store_dwordx4 v[36:37], v[32:35], off offset:1024 sc1
	s_cselect_b32 s6, s24, s6
	s_lshl_b32 s6, s6, 7
	v_lshlrev_b32_e32 v32, 16, v40
	v_fma_f32 v34, v12, v32, v8
	v_and_b32_e32 v32, 0xffff0000, v40
	v_fma_f32 v35, v13, v32, v9
	v_lshlrev_b32_e32 v32, 16, v41
	v_fma_f32 v36, v14, v32, v10
	v_and_b32_e32 v32, 0xffff0000, v41
	v_fma_f32 v37, v15, v32, v11
	v_lshlrev_b32_e32 v32, 16, v42
	v_fma_f32 v38, v4, v32, v0
	v_and_b32_e32 v32, 0xffff0000, v42
	v_fma_f32 v39, v5, v32, v1
	v_lshlrev_b32_e32 v32, 16, v43
	v_fma_f32 v40, v6, v32, v2
	v_and_b32_e32 v32, 0xffff0000, v43
	v_fma_f32 v41, v7, v32, v3
	v_lshlrev_b32_e32 v33, 16, v44
	v_lshlrev_b32_e32 v32, 16, v60
	v_pk_mul_f32 v[32:33], v[24:25], v[32:33]
	s_and_b32 s18, s6, 0xff80
	v_add_f32_e32 v33, v33, v34
	v_add_f32_e32 v34, v32, v33
	v_and_b32_e32 v33, 0xffff0000, v44
	v_and_b32_e32 v32, 0xffff0000, v60
	v_pk_mul_f32 v[32:33], v[20:21], v[32:33]
	s_cmpk_lt_u32 s18, 0x8000
	v_add_f32_e32 v33, v33, v35
	v_add_f32_e32 v35, v32, v33
	v_lshlrev_b32_e32 v32, 16, v61
	v_lshlrev_b32_e32 v33, 16, v45
	v_pk_mul_f32 v[32:33], v[26:27], v[32:33]
	s_cselect_b32 s7, s12, 0x780
	v_add_f32_e32 v33, v33, v36
	v_add_f32_e32 v42, v32, v33
	v_and_b32_e32 v33, 0xffff0000, v45
	v_and_b32_e32 v32, 0xffff0000, v61
	v_pk_mul_f32 v[32:33], v[22:23], v[32:33]
	v_mul_f32_e32 v44, 0xbfb8aa3b, v42
	v_add_f32_e32 v33, v33, v37
	v_add_f32_e32 v43, v32, v33
	v_lshlrev_b32_e32 v33, 16, v46
	v_lshlrev_b32_e32 v32, 16, v62
	v_pk_mul_f32 v[32:33], v[28:29], v[32:33]
	v_exp_f32_e32 v44, v44
	v_add_f32_e32 v33, v33, v38
	v_add_f32_e32 v38, v32, v33
	v_and_b32_e32 v33, 0xffff0000, v46
	v_and_b32_e32 v32, 0xffff0000, v62
	v_pk_mul_f32 v[32:33], v[16:17], v[32:33]
	v_lshl_add_u64 v[36:37], s[0:1], 0, v[88:89]
	v_add_f32_e32 v33, v33, v39
	v_add_f32_e32 v39, v32, v33
	v_lshlrev_b32_e32 v32, 16, v63
	v_lshlrev_b32_e32 v33, 16, v47
	v_pk_mul_f32 v[32:33], v[30:31], v[32:33]
	v_lshlrev_b64 v[36:37], 11, v[36:37]
	v_add_f32_e32 v33, v33, v40
	v_add_f32_e32 v40, v32, v33
	v_and_b32_e32 v33, 0xffff0000, v47
	v_and_b32_e32 v32, 0xffff0000, v63
	v_pk_mul_f32 v[32:33], v[18:19], v[32:33]
	v_lshl_add_u64 v[36:37], v[98:99], 0, v[36:37]
; __device__ __forceinline__ unsigned cvt_pk(float lo, float hi) { unsigned r; asm volatile("v_cvt_pk_bf16_f32 %0, %1, %2" : "=v"(r) : "v"(lo), "v"(hi)); return r; }
; __device__ __forceinline__ float bflo(unsigned w) { return __uint_as_float(w << 16); }
; __device__ __forceinline__ float bfhi(unsigned w) { return __uint_as_float(w & 0xffff0000u); }
; __device__ __forceinline__ float silu(float x) { return x * sigm(x); }
; __device__ void phase_mix(const Params& p, unsigned char* smem) {
;     ...
;             for (int i = 0; i < 4; ++i) { const int tl = (tid >> 4) + 32 * i; const size_t r = (size_t)r0 + tl;
;                 float a[8];
; #pragma unroll
;                 for (int e = 0; e < 8; ++e) a[e] = cb[e];
; #pragma unroll
;                 for (int j = 0; j < 3; ++j) { const u32x4 v = creg[i][j];
;                     a[0] += bflo(v.x) * cw[j][0]; a[1] += bfhi(v.x) * cw[j][1]; a[2] += bflo(v.y) * cw[j][2]; a[3] += bfhi(v.y) * cw[j][3];
;                     a[4] += bflo(v.z) * cw[j][4]; a[5] += bfhi(v.z) * cw[j][5]; a[6] += bflo(v.w) * cw[j][6]; a[7] += bfhi(v.w) * cw[j][7]; }
;                 u32x4 w; w.x = cvt_pk(silu(a[0]), silu(a[1])); w.y = cvt_pk(silu(a[2]), silu(a[3])); w.z = cvt_pk(silu(a[4]), silu(a[5])); w.w = cvt_pk(silu(a[6]), silu(a[7]));
;                 *(u32x4*)(As + swz(tl, ch)) = w; *(u32x4*)(CAT0 + r * 1024 + 512 + cc) = w; }
	v_add_f32_e32 v33, v33, v41
	v_add_f32_e32 v41, v32, v33
	v_mul_f32_e32 v32, 0xbfb8aa3b, v34
	v_exp_f32_e32 v32, v32
	v_mul_f32_e32 v33, 0xbfb8aa3b, v35
	v_exp_f32_e32 v33, v33
	s_cselect_b32 s15, s11, 0x800
	v_add_f32_e32 v32, 1.0, v32
	v_rcp_f32_e32 v32, v32
	v_add_f32_e32 v33, 1.0, v33
	v_rcp_f32_e32 v33, v33
	s_and_b32 s19, s7, s6
	v_mul_f32_e32 v32, v34, v32
	v_mul_f32_e32 v34, 0xbfb8aa3b, v43
	v_mul_f32_e32 v33, v35, v33
	v_exp_f32_e32 v34, v34
	v_mul_f32_e32 v35, 0xbfb8aa3b, v38
	v_cvt_pk_bf16_f32 v32, v32, v33
	v_add_f32_e32 v33, 1.0, v44
	v_exp_f32_e32 v35, v35
	v_rcp_f32_e32 v33, v33
	v_add_f32_e32 v34, 1.0, v34
	v_rcp_f32_e32 v34, v34
	v_add_f32_e32 v35, 1.0, v35
	v_mul_f32_e32 v33, v42, v33
	v_rcp_f32_e32 v35, v35
	v_mul_f32_e32 v42, 0xbfb8aa3b, v39
	v_exp_f32_e32 v42, v42
	v_mul_f32_e32 v34, v43, v34
	v_cvt_pk_bf16_f32 v33, v33, v34
	v_mul_f32_e32 v34, v38, v35
	v_mul_f32_e32 v38, 0xbfb8aa3b, v40
	v_add_f32_e32 v35, 1.0, v42
	v_exp_f32_e32 v38, v38
	v_mul_f32_e32 v42, 0xbfb8aa3b, v41
	v_exp_f32_e32 v42, v42
	v_rcp_f32_e32 v35, v35
	v_add_f32_e32 v38, 1.0, v38
	v_rcp_f32_e32 v38, v38
	v_add_f32_e32 v42, 1.0, v42
	v_rcp_f32_e32 v42, v42
	v_mul_f32_e32 v35, v39, v35
	v_cvt_pk_bf16_f32 v34, v34, v35
	v_mul_f32_e32 v35, v40, v38
	v_mul_f32_e32 v38, v41, v42
	v_cvt_pk_bf16_f32 v35, v35, v38
	ds_write_b128 v111, v[32:35]
	global_store_dwordx4 v[36:37], v[32:35], off offset:1024 sc1
	s_add_i32 s20, s19, -1
	s_add_u32 s6, s18, -1
	v_lshlrev_b32_e32 v32, 16, v52
	v_fma_f32 v34, v12, v32, v8
	v_and_b32_e32 v32, 0xffff0000, v52
	v_fma_f32 v35, v13, v32, v9
	v_lshlrev_b32_e32 v32, 16, v53
	v_fma_f32 v36, v14, v32, v10
	v_and_b32_e32 v32, 0xffff0000, v53
	v_fma_f32 v37, v15, v32, v11
	v_lshlrev_b32_e32 v32, 16, v54
	v_fma_f32 v38, v4, v32, v0
	v_and_b32_e32 v32, 0xffff0000, v54
	v_fma_f32 v39, v5, v32, v1
	v_lshlrev_b32_e32 v32, 16, v55
	v_fma_f32 v40, v6, v32, v2
	v_and_b32_e32 v32, 0xffff0000, v55
	v_fma_f32 v41, v7, v32, v3
	v_lshlrev_b32_e32 v33, 16, v56
	v_lshlrev_b32_e32 v32, 16, v72
	v_pk_mul_f32 v[32:33], v[24:25], v[32:33]
	s_addc_u32 s7, 0, -1
	v_add_f32_e32 v33, v33, v34
	v_add_f32_e32 v34, v32, v33
	v_and_b32_e32 v33, 0xffff0000, v56
	v_and_b32_e32 v32, 0xffff0000, v72
	v_pk_mul_f32 v[32:33], v[20:21], v[32:33]
	s_nop 0
	v_add_f32_e32 v33, v33, v35
	v_add_f32_e32 v35, v32, v33
	v_lshlrev_b32_e32 v32, 16, v73
	v_lshlrev_b32_e32 v33, 16, v57
	v_pk_mul_f32 v[32:33], v[26:27], v[32:33]
	s_nop 0
	v_add_f32_e32 v33, v33, v36
	v_add_f32_e32 v42, v32, v33
	v_and_b32_e32 v33, 0xffff0000, v57
	v_and_b32_e32 v32, 0xffff0000, v73
	v_pk_mul_f32 v[32:33], v[22:23], v[32:33]
	v_mul_f32_e32 v44, 0xbfb8aa3b, v42
	v_add_f32_e32 v33, v33, v37
	v_add_f32_e32 v43, v32, v33
	v_lshlrev_b32_e32 v33, 16, v58
	v_lshlrev_b32_e32 v32, 16, v74
	v_pk_mul_f32 v[32:33], v[28:29], v[32:33]
	v_exp_f32_e32 v44, v44
	v_add_f32_e32 v33, v33, v38
	v_add_f32_e32 v38, v32, v33
	v_and_b32_e32 v33, 0xffff0000, v58
	v_and_b32_e32 v32, 0xffff0000, v74
	v_pk_mul_f32 v[32:33], v[16:17], v[32:33]
	v_lshl_add_u64 v[36:37], s[0:1], 0, v[90:91]
	v_add_f32_e32 v33, v33, v39
	v_add_f32_e32 v39, v32, v33
	v_lshlrev_b32_e32 v32, 16, v75
	v_lshlrev_b32_e32 v33, 16, v59
	v_pk_mul_f32 v[32:33], v[30:31], v[32:33]
	v_lshlrev_b64 v[36:37], 11, v[36:37]
	v_add_f32_e32 v33, v33, v40
	v_add_f32_e32 v40, v32, v33
	v_and_b32_e32 v33, 0xffff0000, v59
	v_and_b32_e32 v32, 0xffff0000, v75
	v_pk_mul_f32 v[32:33], v[18:19], v[32:33]
	v_lshl_add_u64 v[36:37], v[98:99], 0, v[36:37]
	v_add_f32_e32 v33, v33, v41
	v_add_f32_e32 v41, v32, v33
	v_mul_f32_e32 v32, 0xbfb8aa3b, v34
	v_exp_f32_e32 v32, v32
	v_mul_f32_e32 v33, 0xbfb8aa3b, v35
	v_exp_f32_e32 v33, v33
	v_add_f32_e32 v32, 1.0, v32
	v_rcp_f32_e32 v32, v32
	v_add_f32_e32 v33, 1.0, v33
	v_rcp_f32_e32 v33, v33
	v_mul_f32_e32 v32, v34, v32
	v_mul_f32_e32 v34, 0xbfb8aa3b, v43
	v_mul_f32_e32 v33, v35, v33
	v_exp_f32_e32 v34, v34
	v_mul_f32_e32 v35, 0xbfb8aa3b, v38
	v_cvt_pk_bf16_f32 v32, v32, v33
	v_add_f32_e32 v33, 1.0, v44
	v_exp_f32_e32 v35, v35
	v_rcp_f32_e32 v33, v33
	v_add_f32_e32 v34, 1.0, v34
	v_rcp_f32_e32 v34, v34
	v_add_f32_e32 v35, 1.0, v35
	v_mul_f32_e32 v33, v42, v33
	v_rcp_f32_e32 v35, v35
	v_mul_f32_e32 v42, 0xbfb8aa3b, v39
	v_exp_f32_e32 v42, v42
	v_mul_f32_e32 v34, v43, v34
	v_cvt_pk_bf16_f32 v33, v33, v34
	v_mul_f32_e32 v34, v38, v35
; __device__ __forceinline__ unsigned cvt_pk(float lo, float hi) { unsigned r; asm volatile("v_cvt_pk_bf16_f32 %0, %1, %2" : "=v"(r) : "v"(lo), "v"(hi)); return r; }
; __device__ __forceinline__ float bflo(unsigned w) { return __uint_as_float(w << 16); }
; __device__ __forceinline__ float bfhi(unsigned w) { return __uint_as_float(w & 0xffff0000u); }
; __device__ __forceinline__ float silu(float x) { return x * sigm(x); }
; __device__ void phase_mix(const Params& p, unsigned char* smem) {
;     ...
;             for (int i = 0; i < 4; ++i) { const int tl = (tid >> 4) + 32 * i; const size_t r = (size_t)r0 + tl;
;                 float a[8];
; #pragma unroll
;                 for (int e = 0; e < 8; ++e) a[e] = cb[e];
; #pragma unroll
;                 for (int j = 0; j < 3; ++j) { const u32x4 v = creg[i][j];
;                     a[0] += bflo(v.x) * cw[j][0]; a[1] += bfhi(v.x) * cw[j][1]; a[2] += bflo(v.y) * cw[j][2]; a[3] += bfhi(v.y) * cw[j][3];
;                     a[4] += bflo(v.z) * cw[j][4]; a[5] += bfhi(v.z) * cw[j][5]; a[6] += bflo(v.w) * cw[j][6]; a[7] += bfhi(v.w) * cw[j][7]; }
;                 u32x4 w; w.x = cvt_pk(silu(a[0]), silu(a[1])); w.y = cvt_pk(silu(a[2]), silu(a[3])); w.z = cvt_pk(silu(a[4]), silu(a[5])); w.w = cvt_pk(silu(a[6]), silu(a[7]));
;                 *(u32x4*)(As + swz(tl, ch)) = w; *(u32x4*)(CAT0 + r * 1024 + 512 + cc) = w; }
;             __syncthreads();
;             CLOAD((tile_ + tstep < tlim) ? tile_ + tstep : tile_);
	v_mul_f32_e32 v38, 0xbfb8aa3b, v40
	v_add_f32_e32 v35, 1.0, v42
	v_exp_f32_e32 v38, v38
	v_mul_f32_e32 v42, 0xbfb8aa3b, v41
	v_exp_f32_e32 v42, v42
	v_rcp_f32_e32 v35, v35
	v_add_f32_e32 v38, 1.0, v38
	v_rcp_f32_e32 v38, v38
	v_add_f32_e32 v42, 1.0, v42
	v_rcp_f32_e32 v42, v42
	v_mul_f32_e32 v35, v39, v35
	v_cvt_pk_bf16_f32 v34, v34, v35
	v_mul_f32_e32 v35, v40, v38
	v_mul_f32_e32 v38, v41, v42
	v_cvt_pk_bf16_f32 v35, v35, v38
	ds_write_b128 v112, v[32:35]
	global_store_dwordx4 v[36:37], v[32:35], off offset:1024 sc1
	s_nop 1
	v_lshlrev_b32_e32 v32, 16, v64
	v_fma_f32 v34, v12, v32, v8
	v_and_b32_e32 v32, 0xffff0000, v64
	v_fma_f32 v35, v13, v32, v9
	v_lshlrev_b32_e32 v32, 16, v65
	v_fma_f32 v36, v14, v32, v10
	v_and_b32_e32 v32, 0xffff0000, v65
	v_fma_f32 v37, v15, v32, v11
	v_lshlrev_b32_e32 v32, 16, v66
	v_fma_f32 v38, v4, v32, v0
	v_and_b32_e32 v32, 0xffff0000, v66
	v_fma_f32 v39, v5, v32, v1
	v_lshlrev_b32_e32 v32, 16, v67
	v_fma_f32 v40, v6, v32, v2
	v_and_b32_e32 v32, 0xffff0000, v67
	v_fma_f32 v41, v7, v32, v3
	v_lshlrev_b32_e32 v33, 16, v68
	v_lshlrev_b32_e32 v32, 16, v76
	v_pk_mul_f32 v[32:33], v[24:25], v[32:33]
	s_nop 0
	v_add_f32_e32 v33, v33, v34
	v_add_f32_e32 v34, v32, v33
	v_and_b32_e32 v33, 0xffff0000, v68
	v_and_b32_e32 v32, 0xffff0000, v76
	v_pk_mul_f32 v[32:33], v[20:21], v[32:33]
	s_nop 0
	v_add_f32_e32 v33, v33, v35
	v_add_f32_e32 v35, v32, v33
	v_lshlrev_b32_e32 v32, 16, v77
	v_lshlrev_b32_e32 v33, 16, v69
	v_pk_mul_f32 v[32:33], v[26:27], v[32:33]
	s_nop 0
	v_add_f32_e32 v33, v33, v36
	v_add_f32_e32 v42, v32, v33
	v_and_b32_e32 v33, 0xffff0000, v69
	v_and_b32_e32 v32, 0xffff0000, v77
	v_pk_mul_f32 v[32:33], v[22:23], v[32:33]
	v_mul_f32_e32 v44, 0xbfb8aa3b, v42
	v_add_f32_e32 v33, v33, v37
	v_add_f32_e32 v43, v32, v33
	v_lshlrev_b32_e32 v33, 16, v70
	v_lshlrev_b32_e32 v32, 16, v78
	v_pk_mul_f32 v[32:33], v[28:29], v[32:33]
	v_exp_f32_e32 v44, v44
	v_add_f32_e32 v33, v33, v38
	v_add_f32_e32 v38, v32, v33
	v_and_b32_e32 v33, 0xffff0000, v70
	v_and_b32_e32 v32, 0xffff0000, v78
	v_pk_mul_f32 v[32:33], v[16:17], v[32:33]
	v_lshl_add_u64 v[36:37], s[0:1], 0, v[92:93]
	v_add_f32_e32 v33, v33, v39
	v_add_f32_e32 v39, v32, v33
	v_lshlrev_b32_e32 v32, 16, v79
	v_lshlrev_b32_e32 v33, 16, v71
	v_pk_mul_f32 v[32:33], v[30:31], v[32:33]
	v_lshlrev_b64 v[36:37], 11, v[36:37]
	v_add_f32_e32 v33, v33, v40
	v_add_f32_e32 v40, v32, v33
	v_and_b32_e32 v33, 0xffff0000, v71
	v_and_b32_e32 v32, 0xffff0000, v79
	v_pk_mul_f32 v[32:33], v[18:19], v[32:33]
	v_lshl_add_u64 v[36:37], v[98:99], 0, v[36:37]
	v_add_f32_e32 v33, v33, v41
	v_add_f32_e32 v41, v32, v33
	v_mul_f32_e32 v32, 0xbfb8aa3b, v34
	v_mul_f32_e32 v33, 0xbfb8aa3b, v35
	v_exp_f32_e32 v32, v32
	v_exp_f32_e32 v33, v33
	v_add_f32_e32 v32, 1.0, v32
	v_add_f32_e32 v33, 1.0, v33
	v_rcp_f32_e32 v32, v32
	v_rcp_f32_e32 v33, v33
	v_mul_f32_e32 v32, v34, v32
	v_mul_f32_e32 v33, v35, v33
	v_mul_f32_e32 v34, 0xbfb8aa3b, v43
	v_cvt_pk_bf16_f32 v32, v32, v33
	v_add_f32_e32 v33, 1.0, v44
	v_exp_f32_e32 v34, v34
	v_mul_f32_e32 v35, 0xbfb8aa3b, v38
	v_rcp_f32_e32 v33, v33
	v_exp_f32_e32 v35, v35
	v_add_f32_e32 v34, 1.0, v34
	v_rcp_f32_e32 v34, v34
	v_mul_f32_e32 v33, v42, v33
	v_add_f32_e32 v35, 1.0, v35
	v_mul_f32_e32 v42, 0xbfb8aa3b, v39
	v_rcp_f32_e32 v35, v35
	v_exp_f32_e32 v42, v42
	v_mul_f32_e32 v34, v43, v34
	v_cvt_pk_bf16_f32 v33, v33, v34
	v_mul_f32_e32 v34, v38, v35
	v_add_f32_e32 v35, 1.0, v42
	v_mul_f32_e32 v38, 0xbfb8aa3b, v40
	v_mul_f32_e32 v42, 0xbfb8aa3b, v41
	v_exp_f32_e32 v38, v38
	v_exp_f32_e32 v42, v42
	v_rcp_f32_e32 v35, v35
	v_add_f32_e32 v38, 1.0, v38
	v_add_f32_e32 v42, 1.0, v42
	v_rcp_f32_e32 v38, v38
	v_rcp_f32_e32 v42, v42
	v_mul_f32_e32 v35, v39, v35
	v_cvt_pk_bf16_f32 v34, v34, v35
	v_mul_f32_e32 v35, v40, v38
	v_mul_f32_e32 v38, v41, v42
	v_add_u32_e32 v42, s20, v84
	v_cvt_pk_bf16_f32 v35, v35, v38
	global_store_dwordx4 v[36:37], v[32:35], off offset:1024 sc1
	v_lshl_add_u64 v[40:41], s[6:7], 0, v[84:85]
	v_cmp_gt_u32_e32 vcc, s15, v42
	v_mov_b32_e32 v36, 0
	v_mov_b32_e32 v37, 0
	v_mov_b32_e32 v38, 0
	v_mov_b32_e32 v39, 0
	ds_write_b128 v113, v[32:35]
	s_waitcnt lgkmcnt(0)
	s_barrier
	s_and_saveexec_b64 s[8:9], vcc
	s_cbranch_execz .LBB0_202
	v_mad_i64_i32 v[32:33], s[22:23], v40, s13, v[100:101]
	global_load_dwordx4 v[36:39], v[32:33], off offset:2048

; __device__ __forceinline__ int crow(int r, int hi) { return (r & 3) + 8 * (r >> 2) + 4 * hi; }
; __device__ __forceinline__ void attn_body(const bf16_t* __restrict__ Qb, const bf16_t* __restrict__ Kh, const bf16_t* __restrict__ Vh, const bf16_t* __restrict__ Zb, ...
;     ...
;     if (hi == 0) li_l[r32] = l_reg; asm volatile("s_waitcnt lgkmcnt(0)" ::: "memory");
;     float rli[16];
; #pragma unroll
;     for (int r = 0; r < 16; ++r) rli[r] = __builtin_amdgcn_rcpf(li_l[crow(r, hi)]);
;     u32x4 zr[8];
; #pragma unroll
;     for (int i = 0; i < 8; ++i) { const int idx = tid + 512 * i; zr[i] = *(const u32x4*)(Zb + (long)(idx >> 4) * LDP + (idx & 15) * 8); }
;     __syncthreads();
;     float* Ol = (float*)lds;
; #pragma unroll
;     for (int r = 0; r < 16; ++r) { const int orow = wid * QBLK + crow(r, hi);
; #pragma unroll
;         for (int d0 = 0; d0 < 4; ++d0) Ol[orow * 132 + d0 * 32 + r32] = o[d0][r] * rli[r]; }
;     __syncthreads();
.LBB0_480:
	s_or_b64 exec, exec, s[6:7]
	s_waitcnt lgkmcnt(0)
	v_add_u32_e32 v72, v66, v184
	ds_read_b128 v[64:67], v72
	ds_read_b128 v[68:71], v72 offset:32
	v_mov_b32_e32 v189, v185
	v_lshl_or_b32 v125, v199, 2, v202
	v_lshlrev_b32_e32 v126, 2, v201
	s_waitcnt lgkmcnt(1)
	v_rcp_f32_e32 v85, v64
	v_rcp_f32_e32 v110, v65
	v_rcp_f32_e32 v111, v66
	v_rcp_f32_e32 v112, v67
	s_waitcnt lgkmcnt(0)
	v_rcp_f32_e32 v113, v68
	ds_read_b128 v[64:67], v72 offset:64
	v_rcp_f32_e32 v114, v69
	v_rcp_f32_e32 v115, v70
	v_rcp_f32_e32 v116, v71
	ds_read_b128 v[68:71], v72 offset:96
	s_waitcnt lgkmcnt(1)
	v_rcp_f32_e32 v117, v64
	v_rcp_f32_e32 v118, v65
	v_lshl_add_u64 v[64:65], s[16:17], 0, v[188:189]
	v_rcp_f32_e32 v119, v66
	s_waitcnt lgkmcnt(0)
	v_rcp_f32_e32 v121, v68
	v_add_u32_e32 v68, 0x200, v200
	v_rcp_f32_e32 v120, v67
	v_mad_i64_i32 v[66:67], s[16:17], v186, s30, v[64:65]
	v_ashrrev_i32_e32 v108, 4, v68
	v_rcp_f32_e32 v122, v69
	v_mad_i64_i32 v[68:69], s[16:17], v108, s30, v[64:65]
	global_load_dwordx4 v[96:99], v[66:67], off offset:3072
	global_load_dwordx4 v[100:103], v[68:69], off offset:3072
	v_add_u32_e32 v66, 0x400, v200
	v_ashrrev_i32_e32 v94, 4, v66
	v_add_u32_e32 v68, 0x600, v200
	v_mad_i64_i32 v[66:67], s[16:17], v94, s30, v[64:65]
	v_ashrrev_i32_e32 v92, 4, v68
	v_mad_i64_i32 v[68:69], s[16:17], v92, s30, v[64:65]
	global_load_dwordx4 v[104:107], v[66:67], off offset:3072
	global_load_dwordx4 v[80:83], v[68:69], off offset:3072
	v_add_u32_e32 v66, 0x800, v200
	v_add_u32_e32 v68, 0xa00, v200
	v_ashrrev_i32_e32 v90, 4, v66
	v_ashrrev_i32_e32 v88, 4, v68
	v_mad_i64_i32 v[66:67], s[16:17], v90, s30, v[64:65]
	v_mad_i64_i32 v[68:69], s[16:17], v88, s30, v[64:65]
	global_load_dwordx4 v[76:79], v[66:67], off offset:3072
	global_load_dwordx4 v[72:75], v[68:69], off offset:3072
	v_add_u32_e32 v66, 0xc00, v200
	v_add_u32_e32 v68, 0xe00, v200
	v_ashrrev_i32_e32 v86, 4, v66
	v_ashrrev_i32_e32 v84, 4, v68
	v_mul_lo_u32 v125, v125, s37
	v_mad_i64_i32 v[66:67], s[16:17], v86, s30, v[64:65]
	v_mad_i64_i32 v[64:65], s[16:17], v84, s30, v[64:65]
	v_add3_u32 v125, 0, v126, v125
	v_mul_f32_e32 v0, v0, v85
	v_mul_f32_e32 v16, v16, v85
	v_rcp_f32_e32 v123, v70
	v_rcp_f32_e32 v124, v71
	global_load_dwordx4 v[68:71], v[66:67], off offset:3072
	s_nop 0
	global_load_dwordx4 v[64:67], v[64:65], off offset:3072
	s_barrier
	ds_write2_b32 v125, v0, v16 offset1:32
	v_mul_f32_e32 v0, v32, v85
	v_mul_f32_e32 v16, v48, v85
	ds_write2_b32 v125, v0, v16 offset0:64 offset1:96
	v_mul_f32_e32 v0, v1, v110
	v_mul_f32_e32 v1, v17, v110
	ds_write2_b32 v125, v0, v1 offset0:132 offset1:164
	v_mul_f32_e32 v0, v33, v110
	v_mul_f32_e32 v1, v49, v110
	ds_write2_b32 v125, v0, v1 offset0:196 offset1:228
	v_mul_f32_e32 v0, v2, v111
	v_mul_f32_e32 v1, v18, v111
	v_add_u32_e32 v2, 0x400, v125
	ds_write2_b32 v2, v0, v1 offset0:8 offset1:40
	v_mul_f32_e32 v0, v34, v111
	v_mul_f32_e32 v1, v50, v111
	ds_write2_b32 v2, v0, v1 offset0:72 offset1:104
	v_mul_f32_e32 v0, v3, v112
	v_mul_f32_e32 v1, v19, v112
	ds_write2_b32 v2, v0, v1 offset0:140 offset1:172
	v_mul_f32_e32 v0, v35, v112
	v_mul_f32_e32 v1, v51, v112
	ds_write2_b32 v2, v0, v1 offset0:204 offset1:236
	v_mul_f32_e32 v0, v4, v113
	v_mul_f32_e32 v1, v20, v113
	v_add_u32_e32 v2, 0x1000, v125
	ds_write2_b32 v2, v0, v1 offset0:32 offset1:64
	v_mul_f32_e32 v0, v36, v113
	v_mul_f32_e32 v1, v52, v113
	ds_write2_b32 v2, v0, v1 offset0:96 offset1:128
	v_mul_f32_e32 v0, v5, v114
	v_mul_f32_e32 v1, v21, v114
	ds_write2_b32 v2, v0, v1 offset0:164 offset1:196
	v_mul_f32_e32 v0, v37, v114
	v_mul_f32_e32 v1, v53, v114
	v_add_u32_e32 v2, 0x1200, v125
	ds_write2_b32 v2, v0, v1 offset0:100 offset1:132
	v_mul_f32_e32 v0, v6, v115
	v_mul_f32_e32 v1, v22, v115
	v_add_u32_e32 v2, 0x1400, v125
	ds_write2_b32 v2, v0, v1 offset0:40 offset1:72
	v_mul_f32_e32 v0, v38, v115
	v_mul_f32_e32 v1, v54, v115
	ds_write2_b32 v2, v0, v1 offset0:104 offset1:136
	v_mul_f32_e32 v0, v7, v116
	v_mul_f32_e32 v1, v23, v116
	ds_write2_b32 v2, v0, v1 offset0:172 offset1:204
	v_mul_f32_e32 v0, v39, v116
	v_mul_f32_e32 v1, v55, v116
	v_add_u32_e32 v2, 0x1600, v125
	ds_write2_b32 v2, v0, v1 offset0:108 offset1:140
	v_mul_f32_e32 v0, v8, v117
	v_mul_f32_e32 v1, v24, v117
	v_add_u32_e32 v2, 0x2000, v125
	ds_write2_b32 v2, v0, v1 offset0:64 offset1:96
	v_mul_f32_e32 v0, v40, v117
	v_mul_f32_e32 v1, v56, v117
	ds_write2_b32 v2, v0, v1 offset0:128 offset1:160
	v_mul_f32_e32 v0, v9, v118
	v_mul_f32_e32 v1, v25, v118
	ds_write2_b32 v2, v0, v1 offset0:196 offset1:228
	v_mul_f32_e32 v0, v41, v118
	v_mul_f32_e32 v1, v57, v118
	v_add_u32_e32 v2, 0x2400, v125
	ds_write2_b32 v2, v0, v1 offset0:4 offset1:36
	v_mul_f32_e32 v0, v10, v119
	v_mul_f32_e32 v1, v26, v119
	ds_write2_b32 v2, v0, v1 offset0:72 offset1:104
	v_mul_f32_e32 v0, v42, v119
	v_mul_f32_e32 v1, v58, v119
	ds_write2_b32 v2, v0, v1 offset0:136 offset1:168
	v_mul_f32_e32 v0, v11, v120
	v_mul_f32_e32 v1, v27, v120
	ds_write2_b32 v2, v0, v1 offset0:204 offset1:236
	v_mul_f32_e32 v0, v43, v120
	v_mul_f32_e32 v1, v59, v120
	v_add_u32_e32 v2, 0x2800, v125
	ds_write2_b32 v2, v0, v1 offset0:12 offset1:44
	v_mul_f32_e32 v0, v12, v121
	v_mul_f32_e32 v1, v28, v121
	v_add_u32_e32 v2, 0x3000, v125
	ds_write2_b32 v2, v0, v1 offset0:96 offset1:128
	v_mul_f32_e32 v0, v44, v121
	v_mul_f32_e32 v1, v60, v121
	ds_write2_b32 v2, v0, v1 offset0:160 offset1:192
	v_mul_f32_e32 v0, v13, v122
	v_mul_f32_e32 v1, v29, v122
	v_add_u32_e32 v2, 0x3200, v125
	ds_write2_b32 v2, v0, v1 offset0:100 offset1:132
	v_mul_f32_e32 v0, v45, v122
	v_mul_f32_e32 v1, v61, v122
	v_add_u32_e32 v2, 0x3400, v125
	ds_write2_b32 v2, v0, v1 offset0:36 offset1:68
	v_mul_f32_e32 v0, v14, v123
	v_mul_f32_e32 v1, v30, v123
	ds_write2_b32 v2, v0, v1 offset0:104 offset1:136
	v_mul_f32_e32 v0, v46, v123
	v_mul_f32_e32 v1, v62, v123
	ds_write2_b32 v2, v0, v1 offset0:168 offset1:200
	v_mul_f32_e32 v0, v15, v124
	v_mul_f32_e32 v1, v31, v124
	v_add_u32_e32 v2, 0x3600, v125
	v_lshl_add_u32 v8, v198, 2, 0
	ds_write2_b32 v2, v0, v1 offset0:108 offset1:140
	v_mul_f32_e32 v0, v47, v124
	v_mul_f32_e32 v1, v63, v124
	v_add_u32_e32 v2, 0x3800, v125
	v_mad_u64_u32 v[4:5], s[16:17], v186, s37, v[8:9]
	ds_write2_b32 v2, v0, v1 offset0:44 offset1:76
	s_waitcnt lgkmcnt(0)
	s_barrier
; __device__ __forceinline__ unsigned cvt_pk(float lo, float hi) { unsigned r; asm volatile("v_cvt_pk_bf16_f32 %0, %1, %2" : "=v"(r) : "v"(lo), "v"(hi)); return r; }
; __device__ __forceinline__ float bflo(unsigned w) { return __uint_as_float(w << 16); }
; __device__ __forceinline__ float bfhi(unsigned w) { return __uint_as_float(w & 0xffff0000u); }
; __device__ __forceinline__ void attn_body(const bf16_t* __restrict__ Qb, const bf16_t* __restrict__ Kh, const bf16_t* __restrict__ Vh, const bf16_t* __restrict__ Zb, ...
;     ...
; #pragma unroll
;     for (int i = 0; i < 8; ++i) { const int idx = tid + 512 * i, row = idx >> 4, c8 = (idx & 15) * 8;
;         const f32x4 a = *(const f32x4*)(Ol + row * 132 + c8), b = *(const f32x4*)(Ol + row * 132 + c8 + 4);
;         const u32x4 z = zr[i];
;         u32x4 w; w.x = cvt_pk(a[0] * bflo(z.x), a[1] * bfhi(z.x)); w.y = cvt_pk(a[2] * bflo(z.y), a[3] * bfhi(z.y));
;         w.z = cvt_pk(b[0] * bflo(z.z), b[1] * bfhi(z.z)); w.w = cvt_pk(b[2] * bflo(z.w), b[3] * bfhi(z.w));
;         *(u32x4*)(Ob + (long)row * 1024 + c8) = w; }
	ds_read_b128 v[0:3], v4
	s_waitcnt vmcnt(7)
	v_lshlrev_b32_e32 v9, 16, v96
	ds_read_b128 v[4:7], v4 offset:16
	s_lshl_b64 s[6:7], s[8:9], 11
	v_readlane_b32 s20, v254, 46
	s_waitcnt lgkmcnt(1)
	v_mul_f32_e32 v0, v0, v9
	v_and_b32_e32 v9, 0xffff0000, v96
	v_mul_f32_e32 v1, v1, v9
	v_cvt_pk_bf16_f32 v0, v0, v1
	v_lshlrev_b32_e32 v1, 16, v97
	v_mul_f32_e32 v1, v2, v1
	v_and_b32_e32 v2, 0xffff0000, v97
	v_readlane_b32 s21, v254, 47
	s_add_u32 s6, s20, s6
	v_mul_f32_e32 v2, v3, v2
	s_addc_u32 s7, s21, s7
	v_cvt_pk_bf16_f32 v1, v1, v2
	v_lshlrev_b32_e32 v2, 16, v98
	v_and_b32_e32 v3, 0xffff0000, v98
	s_add_u32 s6, s6, s18
	s_waitcnt lgkmcnt(0)
	v_mul_f32_e32 v2, v4, v2
	v_mul_f32_e32 v3, v5, v3
	s_addc_u32 s7, s7, s19
	v_cvt_pk_bf16_f32 v2, v2, v3
	v_lshlrev_b32_e32 v3, 16, v99
	v_and_b32_e32 v4, 0xffff0000, v99
	v_lshl_add_u64 v[10:11], s[6:7], 0, v[188:189]
	v_mul_f32_e32 v3, v6, v3
	v_mul_f32_e32 v4, v7, v4
	v_mad_u64_u32 v[14:15], s[6:7], v108, s37, v[8:9]
	v_cvt_pk_bf16_f32 v3, v3, v4
	ds_read_b128 v[4:7], v14
	v_lshlrev_b64 v[12:13], 11, v[186:187]
	v_lshl_add_u64 v[12:13], v[10:11], 0, v[12:13]
	s_waitcnt vmcnt(6)
	v_lshlrev_b32_e32 v9, 16, v100
	global_store_dwordx4 v[12:13], v[0:3], off sc1
	ds_read_b128 v[0:3], v14 offset:16
	s_waitcnt lgkmcnt(1)
	v_mul_f32_e32 v4, v4, v9
	v_and_b32_e32 v9, 0xffff0000, v100
	v_mul_f32_e32 v5, v5, v9
	v_cvt_pk_bf16_f32 v4, v4, v5
	v_lshlrev_b32_e32 v5, 16, v101
	v_mul_f32_e32 v5, v6, v5
	v_and_b32_e32 v6, 0xffff0000, v101
	v_mul_f32_e32 v6, v7, v6
	v_cvt_pk_bf16_f32 v5, v5, v6
	v_lshlrev_b32_e32 v6, 16, v102
	s_waitcnt lgkmcnt(0)
	v_mul_f32_e32 v0, v0, v6
	v_and_b32_e32 v6, 0xffff0000, v102
	v_mul_f32_e32 v1, v1, v6
	v_cvt_pk_bf16_f32 v6, v0, v1
	v_lshlrev_b32_e32 v0, 16, v103
	v_and_b32_e32 v1, 0xffff0000, v103
	v_mul_f32_e32 v0, v2, v0
	v_mul_f32_e32 v1, v3, v1
	v_mad_u64_u32 v[14:15], s[6:7], v94, s37, v[8:9]
	v_cvt_pk_bf16_f32 v7, v0, v1
	ds_read_b128 v[0:3], v14
	v_ashrrev_i32_e32 v109, 31, v108
	v_lshlrev_b64 v[12:13], 11, v[108:109]
	v_lshl_add_u64 v[12:13], v[10:11], 0, v[12:13]
	s_waitcnt vmcnt(6)
	v_lshlrev_b32_e32 v9, 16, v104
	global_store_dwordx4 v[12:13], v[4:7], off sc1
	ds_read_b128 v[4:7], v14 offset:16
	s_waitcnt lgkmcnt(1)
	v_mul_f32_e32 v0, v0, v9
	v_and_b32_e32 v9, 0xffff0000, v104
	v_mul_f32_e32 v1, v1, v9
	v_cvt_pk_bf16_f32 v0, v0, v1
	v_lshlrev_b32_e32 v1, 16, v105
	v_mul_f32_e32 v1, v2, v1
	v_and_b32_e32 v2, 0xffff0000, v105
	v_mul_f32_e32 v2, v3, v2
	v_cvt_pk_bf16_f32 v1, v1, v2
	v_lshlrev_b32_e32 v2, 16, v106
	v_and_b32_e32 v3, 0xffff0000, v106
	s_waitcnt lgkmcnt(0)
	v_mul_f32_e32 v2, v4, v2
	v_mul_f32_e32 v3, v5, v3
	v_cvt_pk_bf16_f32 v2, v2, v3
	v_lshlrev_b32_e32 v3, 16, v107
	v_and_b32_e32 v4, 0xffff0000, v107
	v_mul_f32_e32 v3, v6, v3
	v_mul_f32_e32 v4, v7, v4
	v_mad_u64_u32 v[14:15], s[6:7], v92, s37, v[8:9]
	v_cvt_pk_bf16_f32 v3, v3, v4
	ds_read_b128 v[4:7], v14
	v_ashrrev_i32_e32 v95, 31, v94
	v_lshlrev_b64 v[12:13], 11, v[94:95]
	v_lshl_add_u64 v[12:13], v[10:11], 0, v[12:13]
	s_waitcnt vmcnt(6)
	v_lshlrev_b32_e32 v9, 16, v80
	global_store_dwordx4 v[12:13], v[0:3], off sc1
	ds_read_b128 v[0:3], v14 offset:16
	s_waitcnt lgkmcnt(1)
	v_mul_f32_e32 v4, v4, v9
	v_and_b32_e32 v9, 0xffff0000, v80
	v_mul_f32_e32 v5, v5, v9
	v_cvt_pk_bf16_f32 v4, v4, v5
	v_lshlrev_b32_e32 v5, 16, v81
	v_mul_f32_e32 v5, v6, v5
	v_and_b32_e32 v6, 0xffff0000, v81
	v_mul_f32_e32 v6, v7, v6
	v_cvt_pk_bf16_f32 v5, v5, v6
	v_lshlrev_b32_e32 v6, 16, v82
	s_waitcnt lgkmcnt(0)
	v_mul_f32_e32 v0, v0, v6
	v_and_b32_e32 v6, 0xffff0000, v82
	v_mul_f32_e32 v1, v1, v6
	v_cvt_pk_bf16_f32 v6, v0, v1
	v_lshlrev_b32_e32 v0, 16, v83
	v_and_b32_e32 v1, 0xffff0000, v83
	v_mul_f32_e32 v0, v2, v0
	v_mul_f32_e32 v1, v3, v1
	v_mad_u64_u32 v[14:15], s[6:7], v90, s37, v[8:9]
	v_cvt_pk_bf16_f32 v7, v0, v1
	ds_read_b128 v[0:3], v14
	v_ashrrev_i32_e32 v93, 31, v92
	v_lshlrev_b64 v[12:13], 11, v[92:93]
	v_lshl_add_u64 v[12:13], v[10:11], 0, v[12:13]
	s_waitcnt vmcnt(6)
; __device__ __forceinline__ unsigned cvt_pk(float lo, float hi) { unsigned r; asm volatile("v_cvt_pk_bf16_f32 %0, %1, %2" : "=v"(r) : "v"(lo), "v"(hi)); return r; }
; __device__ __forceinline__ float bflo(unsigned w) { return __uint_as_float(w << 16); }
; __device__ __forceinline__ float bfhi(unsigned w) { return __uint_as_float(w & 0xffff0000u); }
; __device__ __forceinline__ void attn_body(const bf16_t* __restrict__ Qb, const bf16_t* __restrict__ Kh, const bf16_t* __restrict__ Vh, const bf16_t* __restrict__ Zb, ...
;     ...
; #pragma unroll
;     for (int i = 0; i < 8; ++i) { const int idx = tid + 512 * i, row = idx >> 4, c8 = (idx & 15) * 8;
;         const f32x4 a = *(const f32x4*)(Ol + row * 132 + c8), b = *(const f32x4*)(Ol + row * 132 + c8 + 4);
;         const u32x4 z = zr[i];
;         u32x4 w; w.x = cvt_pk(a[0] * bflo(z.x), a[1] * bfhi(z.x)); w.y = cvt_pk(a[2] * bflo(z.y), a[3] * bfhi(z.y));
;         w.z = cvt_pk(b[0] * bflo(z.z), b[1] * bfhi(z.z)); w.w = cvt_pk(b[2] * bflo(z.w), b[3] * bfhi(z.w));
;         *(u32x4*)(Ob + (long)row * 1024 + c8) = w; }
;     __syncthreads();
	v_lshlrev_b32_e32 v9, 16, v76
	global_store_dwordx4 v[12:13], v[4:7], off sc1
	ds_read_b128 v[4:7], v14 offset:16
	s_waitcnt lgkmcnt(1)
	v_mul_f32_e32 v0, v0, v9
	v_and_b32_e32 v9, 0xffff0000, v76
	v_mul_f32_e32 v1, v1, v9
	v_cvt_pk_bf16_f32 v0, v0, v1
	v_lshlrev_b32_e32 v1, 16, v77
	v_mul_f32_e32 v1, v2, v1
	v_and_b32_e32 v2, 0xffff0000, v77
	v_mul_f32_e32 v2, v3, v2
	v_cvt_pk_bf16_f32 v1, v1, v2
	v_lshlrev_b32_e32 v2, 16, v78
	v_and_b32_e32 v3, 0xffff0000, v78
	s_waitcnt lgkmcnt(0)
	v_mul_f32_e32 v2, v4, v2
	v_mul_f32_e32 v3, v5, v3
	v_cvt_pk_bf16_f32 v2, v2, v3
	v_lshlrev_b32_e32 v3, 16, v79
	v_and_b32_e32 v4, 0xffff0000, v79
	v_mul_f32_e32 v3, v6, v3
	v_mul_f32_e32 v4, v7, v4
	v_mad_u64_u32 v[14:15], s[6:7], v88, s37, v[8:9]
	v_cvt_pk_bf16_f32 v3, v3, v4
	ds_read_b128 v[4:7], v14
	v_ashrrev_i32_e32 v91, 31, v90
	v_lshlrev_b64 v[12:13], 11, v[90:91]
	v_lshl_add_u64 v[12:13], v[10:11], 0, v[12:13]
	s_waitcnt vmcnt(6)
	v_lshlrev_b32_e32 v9, 16, v72
	global_store_dwordx4 v[12:13], v[0:3], off sc1
	ds_read_b128 v[0:3], v14 offset:16
	s_waitcnt lgkmcnt(1)
	v_mul_f32_e32 v4, v4, v9
	v_and_b32_e32 v9, 0xffff0000, v72
	v_mul_f32_e32 v5, v5, v9
	v_cvt_pk_bf16_f32 v4, v4, v5
	v_lshlrev_b32_e32 v5, 16, v73
	v_mul_f32_e32 v5, v6, v5
	v_and_b32_e32 v6, 0xffff0000, v73
	v_mul_f32_e32 v6, v7, v6
	v_cvt_pk_bf16_f32 v5, v5, v6
	v_lshlrev_b32_e32 v6, 16, v74
	s_waitcnt lgkmcnt(0)
	v_mul_f32_e32 v0, v0, v6
	v_and_b32_e32 v6, 0xffff0000, v74
	v_mul_f32_e32 v1, v1, v6
	v_cvt_pk_bf16_f32 v6, v0, v1
	v_lshlrev_b32_e32 v0, 16, v75
	v_and_b32_e32 v1, 0xffff0000, v75
	v_mul_f32_e32 v0, v2, v0
	v_mul_f32_e32 v1, v3, v1
	v_mad_u64_u32 v[14:15], s[6:7], v86, s37, v[8:9]
	v_cvt_pk_bf16_f32 v7, v0, v1
	ds_read_b128 v[0:3], v14
	v_ashrrev_i32_e32 v89, 31, v88
	v_lshlrev_b64 v[12:13], 11, v[88:89]
	v_lshl_add_u64 v[12:13], v[10:11], 0, v[12:13]
	s_waitcnt vmcnt(6)
	v_lshlrev_b32_e32 v9, 16, v68
	global_store_dwordx4 v[12:13], v[4:7], off sc1
	ds_read_b128 v[4:7], v14 offset:16
	s_waitcnt lgkmcnt(1)
	v_mul_f32_e32 v0, v0, v9
	v_and_b32_e32 v9, 0xffff0000, v68
	v_mul_f32_e32 v1, v1, v9
	v_cvt_pk_bf16_f32 v0, v0, v1
	v_lshlrev_b32_e32 v1, 16, v69
	v_mul_f32_e32 v1, v2, v1
	v_and_b32_e32 v2, 0xffff0000, v69
	v_mul_f32_e32 v2, v3, v2
	v_cvt_pk_bf16_f32 v1, v1, v2
	v_lshlrev_b32_e32 v2, 16, v70
	v_and_b32_e32 v3, 0xffff0000, v70
	s_waitcnt lgkmcnt(0)
	v_mul_f32_e32 v2, v4, v2
	v_mul_f32_e32 v3, v5, v3
	v_cvt_pk_bf16_f32 v2, v2, v3
	v_lshlrev_b32_e32 v3, 16, v71
	v_and_b32_e32 v4, 0xffff0000, v71
	v_mul_f32_e32 v3, v6, v3
	v_mul_f32_e32 v4, v7, v4
	v_mad_u64_u32 v[8:9], s[6:7], v84, s37, v[8:9]
	v_cvt_pk_bf16_f32 v3, v3, v4
	ds_read_b128 v[4:7], v8
	v_ashrrev_i32_e32 v87, 31, v86
	v_lshlrev_b64 v[12:13], 11, v[86:87]
	v_lshl_add_u64 v[12:13], v[10:11], 0, v[12:13]
	global_store_dwordx4 v[12:13], v[0:3], off sc1
	ds_read_b128 v[0:3], v8 offset:16
	s_waitcnt vmcnt(7)
	v_lshlrev_b32_e32 v8, 16, v64
	s_waitcnt lgkmcnt(1)
	v_mul_f32_e32 v4, v4, v8
	v_and_b32_e32 v8, 0xffff0000, v64
	v_mul_f32_e32 v5, v5, v8
	v_cvt_pk_bf16_f32 v4, v4, v5
	v_lshlrev_b32_e32 v5, 16, v65
	v_mul_f32_e32 v5, v6, v5
	v_and_b32_e32 v6, 0xffff0000, v65
	v_mul_f32_e32 v6, v7, v6
	v_cvt_pk_bf16_f32 v5, v5, v6
	v_lshlrev_b32_e32 v6, 16, v66
	s_waitcnt lgkmcnt(0)
	v_mul_f32_e32 v0, v0, v6
	v_and_b32_e32 v6, 0xffff0000, v66
	v_mul_f32_e32 v1, v1, v6
	v_cvt_pk_bf16_f32 v6, v0, v1
	v_lshlrev_b32_e32 v0, 16, v67
	v_and_b32_e32 v1, 0xffff0000, v67
	v_ashrrev_i32_e32 v85, 31, v84
	v_mul_f32_e32 v0, v2, v0
	v_mul_f32_e32 v1, v3, v1
	v_cvt_pk_bf16_f32 v7, v0, v1
	v_lshlrev_b64 v[0:1], 11, v[84:85]
	s_add_i32 s38, s38, 1
	v_lshl_add_u64 v[0:1], v[10:11], 0, v[0:1]
	s_cmp_lg_u32 s38, 8
	global_store_dwordx4 v[0:1], v[4:7], off sc1
	s_barrier
	s_cbranch_scc0 .LBB0_500
